# ah1 + wave-sum reductions in modulate0/rowpass loops: 20 six-hop ds_bpermute chains replaced by DPP row adds + v_readlane cross-row sums
# baseline (speedup 1.0000x reference)
.LBB0_208:
	v_mov_b32_e32 v84, v60
	v_mov_b32_e32 v85, v56
	v_mov_b32_e32 v86, v61
	v_mov_b32_e32 v87, v57
	v_pk_add_f32 v[84:85], v[84:85], v[86:87]
	v_mov_b32_e32 v86, v62
	v_mov_b32_e32 v87, v58
	v_mov_b32_e32 v88, v63
	v_mov_b32_e32 v89, v59
	v_pk_add_f32 v[86:87], v[86:87], v[88:89]
	v_mov_b32_e32 v88, v52
	v_pk_add_f32 v[84:85], v[84:85], v[86:87]
	v_mov_b32_e32 v86, v53
	v_mov_b32_e32 v87, v54
	v_mov_b32_e32 v89, v55
	v_pk_add_f32 v[86:87], v[86:87], v[88:89]
	v_add_f32_e32 v84, 0, v84
	v_pk_add_f32 v[86:87], v[86:87], v[86:87] op_sel:[0,1] op_sel_hi:[1,0]
	v_add_f32_e32 v84, v84, v85
	v_add_f32_e32 v88, v48, v49
	v_add_f32_e32 v90, v50, v51
	v_mov_b32_e32 v85, v44
	v_mov_b32_e32 v87, v45
	v_mov_b32_e32 v89, v46
	v_mov_b32_e32 v91, v47
	v_pk_add_f32 v[84:85], v[84:85], v[86:87]
	v_pk_add_f32 v[86:87], v[88:89], v[90:91]
	v_mov_b32_e32 v88, v40
	v_pk_add_f32 v[84:85], v[84:85], v[86:87]
	v_mov_b32_e32 v86, v41
	v_mov_b32_e32 v87, v42
	v_mov_b32_e32 v89, v43
	v_pk_add_f32 v[86:87], v[86:87], v[88:89]
	v_pk_add_f32 v[84:85], v[84:85], v[84:85] op_sel:[0,1] op_sel_hi:[1,0]
	v_pk_add_f32 v[86:87], v[86:87], v[86:87] op_sel:[0,1] op_sel_hi:[1,0]
	v_add_f32_e32 v88, v36, v37
	v_add_f32_e32 v90, v38, v39
	v_mov_b32_e32 v85, v32
	v_mov_b32_e32 v87, v33
	v_mov_b32_e32 v89, v34
	v_mov_b32_e32 v91, v35
	v_pk_add_f32 v[84:85], v[84:85], v[86:87]
	v_pk_add_f32 v[86:87], v[88:89], v[90:91]
	s_nop 0
	v_pk_add_f32 v[84:85], v[84:85], v[86:87]
	s_nop 0
	v_add_f32_e32 v84, v84, v85
	s_waitcnt lgkmcnt(0)
	s_nop 1
	v_add_f32_dpp v84, v84, v84 quad_perm:[1,0,3,2] row_mask:0xf bank_mask:0xf
	s_nop 1
	v_add_f32_dpp v84, v84, v84 quad_perm:[2,3,0,1] row_mask:0xf bank_mask:0xf
	s_nop 1
	v_add_f32_dpp v84, v84, v84 row_half_mirror row_mask:0xf bank_mask:0xf
	s_nop 1
	v_add_f32_dpp v84, v84, v84 row_ror:8 row_mask:0xf bank_mask:0xf
	s_nop 0
	v_readlane_b32 s100, v84, 0
	v_readlane_b32 s101, v84, 16
	s_nop 0
	v_mov_b32_e32 v85, s100
	v_add_f32_e32 v85, s101, v85
	v_readlane_b32 s100, v84, 32
	v_readlane_b32 s101, v84, 48
	s_nop 0
	v_add_f32_e32 v85, s100, v85
	v_add_f32_e32 v90, s101, v85
	v_fmamk_f32 v61, v90, 0xba000000, v61
	v_fmamk_f32 v57, v90, 0xba000000, v57
	v_fmamk_f32 v63, v90, 0xba000000, v63
	v_fmac_f32_e32 v60, 0xba000000, v90
	v_fmamk_f32 v93, v90, 0xba000000, v59
	v_fmac_f32_e32 v56, 0xba000000, v90
	v_mov_b32_e32 v84, v61
	v_mov_b32_e32 v85, v57
	v_fmamk_f32 v62, v90, 0xba000000, v62
	v_fmamk_f32 v92, v90, 0xba000000, v58
	v_mov_b32_e32 v58, v60
	v_mov_b32_e32 v59, v56
	v_pk_mul_f32 v[84:85], v[84:85], v[84:85]
	v_mov_b32_e32 v86, v63
	v_mov_b32_e32 v87, v93
	v_pk_fma_f32 v[58:59], v[58:59], v[58:59], v[84:85]
	v_mov_b32_e32 v84, v62
	v_mov_b32_e32 v85, v92
	v_pk_mul_f32 v[86:87], v[86:87], v[86:87]
	v_fmamk_f32 v95, v90, 0xba000000, v53
	v_pk_fma_f32 v[84:85], v[84:85], v[84:85], v[86:87]
	v_fmamk_f32 v94, v90, 0xba000000, v52
	v_fmamk_f32 v55, v90, 0xba000000, v55
	v_fmac_f32_e32 v54, 0xba000000, v90
	v_pk_add_f32 v[58:59], v[58:59], v[84:85]
	v_pk_mul_f32 v[52:53], v[54:55], v[54:55]
	v_pk_mul_f32 v[84:85], v[94:95], v[94:95]
	v_fmac_f32_e32 v50, 0xba000000, v90
	v_pk_mov_b32 v[86:87], v[84:85], v[52:53] op_sel:[1,0]
	v_mov_b32_e32 v85, v53
	v_pk_add_f32 v[52:53], v[86:87], v[84:85]
	v_fmamk_f32 v51, v90, 0xba000000, v51
	v_pk_add_f32 v[84:85], v[52:53], v[52:53] op_sel_hi:[0,1]
	v_fmamk_f32 v52, v90, 0xba000000, v48
	v_fmamk_f32 v53, v90, 0xba000000, v49
	v_mul_f32_e32 v48, v52, v52
	v_pk_fma_f32 v[86:87], v[52:53], v[52:53], v[48:49] op_sel_hi:[1,1,0]
	v_mul_f32_e32 v48, v50, v50
	v_pk_add_f32 v[58:59], v[58:59], v[58:59] op_sel_hi:[0,1]
	v_pk_fma_f32 v[88:89], v[50:51], v[50:51], v[48:49] op_sel_hi:[1,1,0]
	v_fmamk_f32 v49, v90, 0xba000000, v47
	v_fmamk_f32 v48, v90, 0xba000000, v46
	v_fmamk_f32 v45, v90, 0xba000000, v45
	v_fmac_f32_e32 v44, 0xba000000, v90
	v_mul_f32_e32 v86, v44, v44
	v_mul_f32_e32 v88, v45, v45
	v_mul_f32_e32 v84, v48, v48
	v_mul_f32_e32 v58, v49, v49
	v_pk_add_f32 v[46:47], v[86:87], v[88:89]
	v_pk_add_f32 v[58:59], v[84:85], v[58:59]
	v_fmamk_f32 v41, v90, 0xba000000, v41
	v_pk_add_f32 v[46:47], v[46:47], v[58:59]
	v_fmamk_f32 v40, v90, 0xba000000, v40
	v_fmamk_f32 v43, v90, 0xba000000, v43
	v_fmac_f32_e32 v42, 0xba000000, v90
	v_pk_add_f32 v[46:47], v[46:47], v[46:47] op_sel_hi:[0,1]
	v_pk_mul_f32 v[58:59], v[42:43], v[42:43]
	v_pk_mul_f32 v[84:85], v[40:41], v[40:41]
	v_fmamk_f32 v36, v90, 0xba000000, v36
	v_pk_mov_b32 v[86:87], v[84:85], v[58:59] op_sel:[1,0]
	v_mov_b32_e32 v85, v59
	v_fmamk_f32 v37, v90, 0xba000000, v37
	v_fmac_f32_e32 v38, 0xba000000, v90
	v_mul_f32_e32 v46, v36, v36
	v_pk_add_f32 v[58:59], v[86:87], v[84:85]
	v_fmamk_f32 v39, v90, 0xba000000, v39
	v_pk_fma_f32 v[84:85], v[36:37], v[36:37], v[46:47] op_sel_hi:[1,1,0]
	v_mul_f32_e32 v46, v38, v38
	v_pk_add_f32 v[58:59], v[58:59], v[58:59] op_sel_hi:[0,1]
	v_pk_fma_f32 v[86:87], v[38:39], v[38:39], v[46:47] op_sel_hi:[1,1,0]
	v_fmamk_f32 v35, v90, 0xba000000, v35
	v_fmamk_f32 v34, v90, 0xba000000, v34
	v_fmamk_f32 v33, v90, 0xba000000, v33
	v_fmac_f32_e32 v32, 0xba000000, v90
	v_mul_f32_e32 v84, v32, v32
	v_mul_f32_e32 v86, v33, v33
	v_mul_f32_e32 v58, v34, v34
	v_mul_f32_e32 v46, v35, v35
	v_pk_add_f32 v[84:85], v[84:85], v[86:87]
	v_pk_add_f32 v[46:47], v[58:59], v[46:47]
	s_nop 0
	v_pk_add_f32 v[46:47], v[84:85], v[46:47]
	s_nop 0
	v_add_f32_e32 v46, v46, v47
	s_waitcnt lgkmcnt(0)
	s_nop 1
	v_add_f32_dpp v46, v46, v46 quad_perm:[1,0,3,2] row_mask:0xf bank_mask:0xf
	s_nop 1
	v_add_f32_dpp v46, v46, v46 quad_perm:[2,3,0,1] row_mask:0xf bank_mask:0xf
	s_nop 1
	v_add_f32_dpp v46, v46, v46 row_half_mirror row_mask:0xf bank_mask:0xf
	s_nop 1
	v_add_f32_dpp v46, v46, v46 row_ror:8 row_mask:0xf bank_mask:0xf
	s_nop 0
	v_readlane_b32 s100, v46, 0
	v_readlane_b32 s101, v46, 16
	s_nop 0
	v_mov_b32_e32 v47, s100
	v_add_f32_e32 v47, s101, v47
	v_readlane_b32 s100, v46, 32
	v_readlane_b32 s101, v46, 48
	s_nop 0
	v_add_f32_e32 v47, s100, v47
	v_add_f32_e32 v46, s101, v47
	v_fmamk_f32 v46, v46, 0x3a000000, v82
	v_mul_f32_e32 v47, 0x4f800000, v46
	v_cmp_gt_f32_e32 vcc, s3, v46
	s_nop 1
	v_cndmask_b32_e32 v46, v46, v47, vcc
	v_sqrt_f32_e32 v47, v46
	s_nop 0
	v_add_u32_e32 v58, -1, v47
	v_fma_f32 v59, -v58, v47, v46
	v_cmp_ge_f32_e64 s[4:5], 0, v59
	v_add_u32_e32 v59, 1, v47
	s_nop 0
	v_cndmask_b32_e64 v58, v47, v58, s[4:5]
	v_fma_f32 v47, -v59, v47, v46
	v_cmp_lt_f32_e64 s[4:5], 0, v47
	s_nop 1
	v_cndmask_b32_e64 v47, v58, v59, s[4:5]
	v_mul_f32_e32 v58, 0x37800000, v47
	v_cndmask_b32_e32 v47, v47, v58, vcc
	v_cmp_class_f32_e32 vcc, v46, v83
	s_nop 1
	v_cndmask_b32_e32 v46, v47, v46, vcc
	v_div_scale_f32 v47, s[4:5], v46, v46, 1.0
	v_rcp_f32_e32 v58, v47
	s_min_i32 s4, s20, 0x4000
	s_and_b32 s4, s4, 0x3ffff000
	v_fma_f32 v59, -v47, v58, 1.0
	v_fmac_f32_e32 v58, v59, v58
	v_div_scale_f32 v59, vcc, 1.0, v46, 1.0
	v_mul_f32_e32 v84, v59, v58
	v_fma_f32 v85, -v47, v84, v59
	v_fmac_f32_e32 v84, v85, v58
	v_fma_f32 v47, -v47, v84, v59
	v_div_fmas_f32 v47, v47, v58, v84
	v_div_fixup_f32 v46, v47, v46, 1.0
	v_lshl_add_u32 v47, s4, 2, v77
	ds_read_b128 v[84:87], v47 offset:8192
	ds_read_b128 v[88:91], v47
	v_pk_mul_f32 v[96:97], v[60:61], v[46:47] op_sel_hi:[1,0]
	ds_read_b128 v[58:61], v47 offset:9216
	v_pk_mul_f32 v[62:63], v[62:63], v[46:47] op_sel_hi:[1,0]
	s_waitcnt lgkmcnt(2)
	v_pk_add_f32 v[100:101], v[84:85], 1.0 op_sel_hi:[1,0]
	v_pk_add_f32 v[98:99], v[86:87], 1.0 op_sel_hi:[1,0]
	ds_read_b128 v[84:87], v47 offset:1024
	s_waitcnt lgkmcnt(2)
	v_pk_fma_f32 v[88:89], v[100:101], v[96:97], v[88:89]
	v_pk_fma_f32 v[62:63], v[98:99], v[62:63], v[90:91]
	v_cvt_pk_bf16_f32 v88, v88, v89
	v_pk_mul_f32 v[56:57], v[56:57], v[46:47] op_sel_hi:[1,0]
	s_waitcnt lgkmcnt(1)
	v_pk_add_f32 v[58:59], v[58:59], 1.0 op_sel_hi:[1,0]
	s_waitcnt lgkmcnt(0)
	v_pk_fma_f32 v[56:57], v[58:59], v[56:57], v[84:85]
	v_cvt_pk_bf16_f32 v89, v62, v63
	v_pk_mul_f32 v[62:63], v[92:93], v[46:47] op_sel_hi:[1,0]
	v_pk_add_f32 v[60:61], v[60:61], 1.0 op_sel_hi:[1,0]
	v_pk_fma_f32 v[60:61], v[60:61], v[62:63], v[86:87]
	v_cvt_pk_bf16_f32 v56, v56, v57
	v_cvt_pk_bf16_f32 v57, v60, v61
	global_store_dwordx2 v[70:71], v[88:89], off
	global_store_dwordx2 v[70:71], v[56:57], off offset:512
	ds_read_b128 v[56:59], v47 offset:10240
	ds_read_b128 v[60:63], v47 offset:2048
	v_pk_mul_f32 v[88:89], v[94:95], v[46:47] op_sel_hi:[1,0]
	v_pk_mul_f32 v[90:91], v[54:55], v[46:47] op_sel_hi:[1,0]
	ds_read_b128 v[84:87], v47 offset:11264
	s_waitcnt lgkmcnt(2)
	v_pk_add_f32 v[92:93], v[56:57], 1.0 op_sel_hi:[1,0]
	v_pk_add_f32 v[58:59], v[58:59], 1.0 op_sel_hi:[1,0]
	s_waitcnt lgkmcnt(1)
	v_pk_fma_f32 v[60:61], v[92:93], v[88:89], v[60:61]
	v_pk_fma_f32 v[58:59], v[58:59], v[90:91], v[62:63]
	ds_read_b128 v[54:57], v47 offset:3072
	v_cvt_pk_bf16_f32 v60, v60, v61
	v_cvt_pk_bf16_f32 v61, v58, v59
	global_store_dwordx2 v[70:71], v[60:61], off offset:1024
	v_pk_mul_f32 v[52:53], v[52:53], v[46:47] op_sel_hi:[1,0]
	s_waitcnt lgkmcnt(1)
	v_pk_add_f32 v[60:61], v[84:85], 1.0 op_sel_hi:[1,0]
	v_pk_mul_f32 v[50:51], v[50:51], v[46:47] op_sel_hi:[1,0]
	s_waitcnt lgkmcnt(0)
	v_pk_fma_f32 v[52:53], v[60:61], v[52:53], v[54:55]
	v_pk_add_f32 v[58:59], v[86:87], 1.0 op_sel_hi:[1,0]
	v_pk_fma_f32 v[50:51], v[58:59], v[50:51], v[56:57]
	v_cvt_pk_bf16_f32 v52, v52, v53
	v_cvt_pk_bf16_f32 v53, v50, v51
	global_store_dwordx2 v[70:71], v[52:53], off offset:1536
	ds_read_b128 v[50:53], v47 offset:12288
	ds_read_b128 v[54:57], v47 offset:4096
	v_pk_mul_f32 v[44:45], v[44:45], v[46:47] op_sel_hi:[1,0]
	v_pk_mul_f32 v[62:63], v[48:49], v[46:47] op_sel_hi:[1,0]
	ds_read_b128 v[58:61], v47 offset:13312
	s_waitcnt lgkmcnt(2)
	v_pk_add_f32 v[84:85], v[50:51], 1.0 op_sel_hi:[1,0]
	v_pk_add_f32 v[52:53], v[52:53], 1.0 op_sel_hi:[1,0]
	s_waitcnt lgkmcnt(1)
	v_pk_fma_f32 v[44:45], v[84:85], v[44:45], v[54:55]
	ds_read_b128 v[48:51], v47 offset:5120
	v_pk_fma_f32 v[52:53], v[52:53], v[62:63], v[56:57]
	v_cvt_pk_bf16_f32 v44, v44, v45
	v_cvt_pk_bf16_f32 v45, v52, v53
	v_pk_mul_f32 v[40:41], v[40:41], v[46:47] op_sel_hi:[1,0]
	s_waitcnt lgkmcnt(1)
	v_pk_add_f32 v[52:53], v[58:59], 1.0 op_sel_hi:[1,0]
	global_store_dwordx2 v[70:71], v[44:45], off offset:2048
	v_pk_mul_f32 v[42:43], v[42:43], v[46:47] op_sel_hi:[1,0]
	v_pk_add_f32 v[44:45], v[60:61], 1.0 op_sel_hi:[1,0]
	s_waitcnt lgkmcnt(0)
	v_pk_fma_f32 v[40:41], v[52:53], v[40:41], v[48:49]
	v_pk_fma_f32 v[42:43], v[44:45], v[42:43], v[50:51]
	v_cvt_pk_bf16_f32 v40, v40, v41
	v_cvt_pk_bf16_f32 v41, v42, v43
	global_store_dwordx2 v[70:71], v[40:41], off offset:2560
	ds_read_b128 v[40:43], v47 offset:14336
	ds_read_b128 v[48:51], v47 offset:6144
	v_pk_mul_f32 v[44:45], v[36:37], v[46:47] op_sel_hi:[1,0]
	v_pk_mul_f32 v[52:53], v[38:39], v[46:47] op_sel_hi:[1,0]
	ds_read_b128 v[36:39], v47 offset:15360
	s_waitcnt lgkmcnt(2)
	v_pk_add_f32 v[56:57], v[40:41], 1.0 op_sel_hi:[1,0]
	v_pk_add_f32 v[54:55], v[42:43], 1.0 op_sel_hi:[1,0]
	s_waitcnt lgkmcnt(1)
	v_pk_fma_f32 v[44:45], v[56:57], v[44:45], v[48:49]
	ds_read_b128 v[40:43], v47 offset:7168
	v_pk_fma_f32 v[50:51], v[54:55], v[52:53], v[50:51]
	v_bfe_u32 v47, v51, 16, 1
	v_add3_u32 v47, v51, v47, s28
	v_pk_mul_f32 v[32:33], v[32:33], v[46:47] op_sel_hi:[1,0]
	s_waitcnt lgkmcnt(1)
	v_pk_add_f32 v[36:37], v[36:37], 1.0 op_sel_hi:[1,0]
	v_pk_mul_f32 v[34:35], v[34:35], v[46:47] op_sel_hi:[1,0]
	s_waitcnt lgkmcnt(0)
	v_pk_fma_f32 v[32:33], v[36:37], v[32:33], v[40:41]
	v_pk_add_f32 v[38:39], v[38:39], 1.0 op_sel_hi:[1,0]
	v_pk_fma_f32 v[34:35], v[38:39], v[34:35], v[42:43]
	v_cvt_pk_bf16_f32 v44, v44, v45
	v_bfe_u32 v45, v50, 16, 1
	v_cvt_pk_bf16_f32 v32, v32, v33
	v_add3_u32 v45, v50, v45, s28
	v_lshrrev_b32_e32 v45, 16, v45
	v_and_or_b32 v45, v47, s29, v45
	v_cvt_pk_bf16_f32 v33, v34, v35
	s_andn2_b64 vcc, exec, s[24:25]
	global_store_dwordx2 v[70:71], v[44:45], off offset:3072
	global_store_dwordx2 v[70:71], v[32:33], off offset:3584
	s_cbranch_vccnz .LBB0_197
	v_mov_b32_e32 v32, v4
	v_mov_b32_e32 v33, v0
	v_mov_b32_e32 v34, v5
	v_mov_b32_e32 v35, v1
	v_pk_add_f32 v[32:33], v[32:33], v[34:35]
	v_mov_b32_e32 v34, v6
	v_mov_b32_e32 v35, v2
	v_mov_b32_e32 v36, v7
	v_mov_b32_e32 v37, v3
	v_pk_add_f32 v[34:35], v[34:35], v[36:37]
	v_mov_b32_e32 v36, v8
	v_pk_add_f32 v[32:33], v[32:33], v[34:35]
	v_mov_b32_e32 v34, v9
	v_mov_b32_e32 v35, v10
	v_mov_b32_e32 v37, v11
	v_pk_add_f32 v[34:35], v[34:35], v[36:37]
	v_add_f32_e32 v33, 0, v33
	v_pk_add_f32 v[34:35], v[34:35], v[34:35] op_sel_hi:[0,1]
	v_add_f32_e32 v33, v32, v33
	v_add_f32_e32 v37, v12, v13
	v_add_f32_e32 v39, v14, v15
	v_mov_b32_e32 v36, v16
	v_mov_b32_e32 v38, v17
	v_mov_b32_e32 v34, v18
	v_mov_b32_e32 v32, v19
	v_pk_add_f32 v[36:37], v[36:37], v[38:39]
	v_pk_add_f32 v[32:33], v[34:35], v[32:33]
	v_mov_b32_e32 v34, v21
	v_pk_add_f32 v[32:33], v[36:37], v[32:33]
	v_mov_b32_e32 v35, v22
	v_mov_b32_e32 v36, v20
	v_mov_b32_e32 v37, v23
	v_pk_add_f32 v[34:35], v[34:35], v[36:37]
	v_pk_add_f32 v[32:33], v[32:33], v[32:33] op_sel_hi:[0,1]
	v_pk_add_f32 v[34:35], v[34:35], v[34:35] op_sel_hi:[0,1]
	v_add_f32_e32 v37, v24, v25
	v_add_f32_e32 v39, v26, v27
	v_mov_b32_e32 v36, v28
	v_mov_b32_e32 v38, v29
	v_mov_b32_e32 v34, v30
	v_mov_b32_e32 v32, v31
	v_pk_add_f32 v[36:37], v[36:37], v[38:39]
	v_pk_add_f32 v[32:33], v[34:35], v[32:33]
	s_ashr_i32 s23, s22, 31
	v_pk_add_f32 v[32:33], v[36:37], v[32:33]
	s_nop 0
	v_add_f32_e32 v32, v32, v33
	s_waitcnt lgkmcnt(0)
	s_nop 1
	v_add_f32_dpp v32, v32, v32 quad_perm:[1,0,3,2] row_mask:0xf bank_mask:0xf
	s_nop 1
	v_add_f32_dpp v32, v32, v32 quad_perm:[2,3,0,1] row_mask:0xf bank_mask:0xf
	s_nop 1
	v_add_f32_dpp v32, v32, v32 row_half_mirror row_mask:0xf bank_mask:0xf
	s_nop 1
	v_add_f32_dpp v32, v32, v32 row_ror:8 row_mask:0xf bank_mask:0xf
	s_nop 0
	v_readlane_b32 s100, v32, 0
	v_readlane_b32 s101, v32, 16
	s_nop 0
	v_mov_b32_e32 v33, s100
	v_add_f32_e32 v33, s101, v33
	v_readlane_b32 s100, v32, 32
	v_readlane_b32 s101, v32, 48
	s_nop 0
	v_add_f32_e32 v33, s100, v33
	v_add_f32_e32 v60, s101, v33
	v_fmamk_f32 v85, v60, 0xba000000, v1
	v_fmamk_f32 v95, v60, 0xba000000, v5
	v_fmamk_f32 v63, v60, 0xba000000, v3
	v_fmamk_f32 v84, v60, 0xba000000, v0
	v_fmamk_f32 v93, v60, 0xba000000, v7
	v_fmamk_f32 v94, v60, 0xba000000, v4
	v_mov_b32_e32 v34, v85
	v_mov_b32_e32 v35, v95
	v_fmamk_f32 v62, v60, 0xba000000, v2
	v_fmamk_f32 v92, v60, 0xba000000, v6
	v_mov_b32_e32 v32, v84
	v_mov_b32_e32 v33, v94
	v_pk_mul_f32 v[34:35], v[34:35], v[34:35]
	v_mov_b32_e32 v36, v63
	v_mov_b32_e32 v37, v93
	v_pk_fma_f32 v[32:33], v[32:33], v[32:33], v[34:35]
	v_mov_b32_e32 v34, v62
	v_mov_b32_e32 v35, v92
	v_pk_mul_f32 v[36:37], v[36:37], v[36:37]
	v_fmamk_f32 v97, v60, 0xba000000, v9
	v_pk_fma_f32 v[34:35], v[34:35], v[34:35], v[36:37]
	v_fmamk_f32 v96, v60, 0xba000000, v8
	v_pk_add_f32 v[32:33], v[32:33], v[34:35]
	v_fmamk_f32 v99, v60, 0xba000000, v11
	v_fmamk_f32 v98, v60, 0xba000000, v10
	v_pk_add_f32 v[32:33], v[32:33], v[32:33] op_sel_hi:[0,1]
	v_pk_mul_f32 v[34:35], v[98:99], v[98:99]
	v_pk_mul_f32 v[36:37], v[96:97], v[96:97]
	v_fmamk_f32 v50, v60, 0xba000000, v12
	v_pk_mov_b32 v[38:39], v[36:37], v[34:35] op_sel:[1,0]
	v_mov_b32_e32 v37, v35
	v_fmamk_f32 v51, v60, 0xba000000, v13
	v_fmamk_f32 v52, v60, 0xba000000, v14
	v_mul_f32_e32 v32, v50, v50
	v_pk_add_f32 v[34:35], v[38:39], v[36:37]
	v_fmamk_f32 v53, v60, 0xba000000, v15
	v_pk_fma_f32 v[36:37], v[50:51], v[50:51], v[32:33] op_sel_hi:[1,1,0]
	v_mul_f32_e32 v32, v52, v52
	v_pk_add_f32 v[34:35], v[34:35], v[34:35] op_sel_hi:[0,1]
	v_pk_fma_f32 v[38:39], v[52:53], v[52:53], v[32:33] op_sel_hi:[1,1,0]
	v_fmamk_f32 v47, v60, 0xba000000, v19
	v_fmamk_f32 v46, v60, 0xba000000, v18
	v_fmamk_f32 v49, v60, 0xba000000, v17
	v_fmamk_f32 v48, v60, 0xba000000, v16
	v_mul_f32_e32 v36, v48, v48
	v_mul_f32_e32 v38, v49, v49
	v_mul_f32_e32 v34, v46, v46
	v_mul_f32_e32 v32, v47, v47
	v_pk_add_f32 v[36:37], v[36:37], v[38:39]
	v_pk_add_f32 v[32:33], v[34:35], v[32:33]
	v_fmamk_f32 v41, v60, 0xba000000, v21
	v_pk_add_f32 v[32:33], v[36:37], v[32:33]
	v_fmamk_f32 v40, v60, 0xba000000, v20
	v_fmamk_f32 v43, v60, 0xba000000, v23
	v_fmamk_f32 v42, v60, 0xba000000, v22
	v_pk_add_f32 v[44:45], v[32:33], v[32:33] op_sel_hi:[0,1]
	v_pk_mul_f32 v[32:33], v[42:43], v[42:43]
	v_pk_mul_f32 v[34:35], v[40:41], v[40:41]
	v_fmamk_f32 v38, v60, 0xba000000, v26
	v_pk_mov_b32 v[36:37], v[34:35], v[32:33] op_sel:[1,0]
	v_mov_b32_e32 v35, v33
	v_pk_add_f32 v[32:33], v[36:37], v[34:35]
	v_fmamk_f32 v36, v60, 0xba000000, v24
	v_pk_add_f32 v[54:55], v[32:33], v[32:33] op_sel_hi:[0,1]
	v_fmamk_f32 v37, v60, 0xba000000, v25
	v_mul_f32_e32 v32, v36, v36
	v_fmamk_f32 v39, v60, 0xba000000, v27
	v_pk_fma_f32 v[56:57], v[36:37], v[36:37], v[32:33] op_sel_hi:[1,1,0]
	v_mul_f32_e32 v32, v38, v38
	v_pk_fma_f32 v[58:59], v[38:39], v[38:39], v[32:33] op_sel_hi:[1,1,0]
	v_fmamk_f32 v33, v60, 0xba000000, v31
	v_fmamk_f32 v32, v60, 0xba000000, v30
	v_fmamk_f32 v35, v60, 0xba000000, v29
	v_fmamk_f32 v34, v60, 0xba000000, v28
	v_mul_f32_e32 v56, v34, v34
	v_mul_f32_e32 v58, v35, v35
	v_mul_f32_e32 v54, v32, v32
	v_mul_f32_e32 v44, v33, v33
	v_pk_add_f32 v[56:57], v[56:57], v[58:59]
	v_pk_add_f32 v[44:45], v[54:55], v[44:45]
	s_nop 0
	v_pk_add_f32 v[44:45], v[56:57], v[44:45]
	s_nop 0
	v_add_f32_e32 v44, v44, v45
	s_waitcnt lgkmcnt(0)
	s_nop 1
	v_add_f32_dpp v44, v44, v44 quad_perm:[1,0,3,2] row_mask:0xf bank_mask:0xf
	s_nop 1
	v_add_f32_dpp v44, v44, v44 quad_perm:[2,3,0,1] row_mask:0xf bank_mask:0xf
	s_nop 1
	v_add_f32_dpp v44, v44, v44 row_half_mirror row_mask:0xf bank_mask:0xf
	s_nop 1
	v_add_f32_dpp v44, v44, v44 row_ror:8 row_mask:0xf bank_mask:0xf
	s_nop 0
	v_readlane_b32 s100, v44, 0
	v_readlane_b32 s101, v44, 16
	s_nop 0
	v_mov_b32_e32 v45, s100
	v_add_f32_e32 v45, s101, v45
	v_readlane_b32 s100, v44, 32
	v_readlane_b32 s101, v44, 48
	s_nop 0
	v_add_f32_e32 v45, s100, v45
	v_add_f32_e32 v44, s101, v45
	v_fmamk_f32 v44, v44, 0x3a000000, v82
	v_mul_f32_e32 v45, 0x4f800000, v44
	v_cmp_gt_f32_e32 vcc, s3, v44
	s_nop 1
	v_cndmask_b32_e32 v44, v44, v45, vcc
	v_sqrt_f32_e32 v45, v44
	s_nop 0
	v_add_u32_e32 v54, -1, v45
	v_fma_f32 v55, -v54, v45, v44
	v_cmp_ge_f32_e64 s[4:5], 0, v55
	v_add_u32_e32 v55, 1, v45
	s_nop 0
	v_cndmask_b32_e64 v54, v45, v54, s[4:5]
	v_fma_f32 v45, -v55, v45, v44
	v_cmp_lt_f32_e64 s[4:5], 0, v45
	s_nop 1
	v_cndmask_b32_e64 v45, v54, v55, s[4:5]
	v_mul_f32_e32 v54, 0x37800000, v45
	v_cndmask_b32_e32 v45, v45, v54, vcc
	v_cmp_class_f32_e32 vcc, v44, v83
	s_nop 1
	v_cndmask_b32_e32 v44, v45, v44, vcc
	v_div_scale_f32 v45, s[4:5], v44, v44, 1.0
	v_rcp_f32_e32 v54, v45
	s_min_i32 s4, s22, 0x4000
	s_and_b32 s8, s4, 0x3ffff000
	s_lshl_b64 s[4:5], s[22:23], 12
	v_fma_f32 v55, -v45, v54, 1.0
	v_fmac_f32_e32 v54, v55, v54
	v_div_scale_f32 v55, vcc, 1.0, v44, 1.0
	v_mul_f32_e32 v56, v55, v54
	v_fma_f32 v57, -v45, v56, v55
	v_fmac_f32_e32 v56, v57, v54
	v_fma_f32 v45, -v45, v56, v55
	v_div_fmas_f32 v45, v45, v54, v56
	v_div_fixup_f32 v44, v45, v44, 1.0
	v_lshl_add_u32 v45, s8, 2, v77
	ds_read_b128 v[54:57], v45 offset:8192
	ds_read_b128 v[58:61], v45
	v_pk_mul_f32 v[100:101], v[84:85], v[44:45] op_sel_hi:[1,0]
	v_pk_mul_f32 v[62:63], v[62:63], v[44:45] op_sel_hi:[1,0]
	ds_read_b128 v[84:87], v45 offset:9216
	ds_read_b128 v[88:91], v45 offset:1024
	s_waitcnt lgkmcnt(3)
	v_pk_add_f32 v[54:55], v[54:55], 1.0 op_sel_hi:[1,0]
	v_pk_add_f32 v[56:57], v[56:57], 1.0 op_sel_hi:[1,0]
	s_waitcnt lgkmcnt(2)
	v_pk_fma_f32 v[54:55], v[54:55], v[100:101], v[58:59]
	v_pk_fma_f32 v[56:57], v[56:57], v[62:63], v[60:61]
	v_cvt_pk_bf16_f32 v58, v54, v55
	v_cvt_pk_bf16_f32 v59, v56, v57
	v_lshl_add_u64 v[54:55], v[68:69], 0, s[4:5]
	v_pk_mul_f32 v[56:57], v[94:95], v[44:45] op_sel_hi:[1,0]
	s_waitcnt lgkmcnt(1)
	v_pk_add_f32 v[62:63], v[84:85], 1.0 op_sel_hi:[1,0]
	global_store_dwordx2 v[54:55], v[58:59], off
	v_pk_mul_f32 v[58:59], v[92:93], v[44:45] op_sel_hi:[1,0]
	v_pk_add_f32 v[60:61], v[86:87], 1.0 op_sel_hi:[1,0]
	s_waitcnt lgkmcnt(0)
	v_pk_fma_f32 v[56:57], v[62:63], v[56:57], v[88:89]
	v_pk_fma_f32 v[58:59], v[60:61], v[58:59], v[90:91]
	v_cvt_pk_bf16_f32 v56, v56, v57
	v_cvt_pk_bf16_f32 v57, v58, v59
	global_store_dwordx2 v[54:55], v[56:57], off offset:512
	ds_read_b128 v[56:59], v45 offset:10240
	ds_read_b128 v[60:63], v45 offset:2048
	v_pk_mul_f32 v[88:89], v[96:97], v[44:45] op_sel_hi:[1,0]
	v_pk_mul_f32 v[90:91], v[98:99], v[44:45] op_sel_hi:[1,0]
	ds_read_b128 v[84:87], v45 offset:11264
	s_waitcnt lgkmcnt(2)
	v_pk_add_f32 v[94:95], v[56:57], 1.0 op_sel_hi:[1,0]
	v_pk_add_f32 v[92:93], v[58:59], 1.0 op_sel_hi:[1,0]
	s_waitcnt lgkmcnt(1)
	v_pk_fma_f32 v[60:61], v[94:95], v[88:89], v[60:61]
	ds_read_b128 v[56:59], v45 offset:3072
	v_bfe_u32 v88, v60, 16, 1
	v_add3_u32 v60, v60, v88, s28
	v_bfe_u32 v88, v61, 16, 1
	v_pk_fma_f32 v[62:63], v[92:93], v[90:91], v[62:63]
	v_lshrrev_b32_e32 v60, 16, v60
	v_add3_u32 v61, v61, v88, s28
	v_and_or_b32 v60, v61, s29, v60
	v_cvt_pk_bf16_f32 v61, v62, v63
	v_pk_mul_f32 v[50:51], v[50:51], v[44:45] op_sel_hi:[1,0]
	s_waitcnt lgkmcnt(1)
	v_pk_add_f32 v[62:63], v[84:85], 1.0 op_sel_hi:[1,0]
	global_store_dwordx2 v[54:55], v[60:61], off offset:1024
	s_waitcnt lgkmcnt(0)
	v_pk_fma_f32 v[50:51], v[62:63], v[50:51], v[56:57]
	v_pk_mul_f32 v[52:53], v[52:53], v[44:45] op_sel_hi:[1,0]
	v_pk_add_f32 v[60:61], v[86:87], 1.0 op_sel_hi:[1,0]
	v_pk_fma_f32 v[52:53], v[60:61], v[52:53], v[58:59]
	v_cvt_pk_bf16_f32 v50, v50, v51
	v_cvt_pk_bf16_f32 v51, v52, v53
	global_store_dwordx2 v[54:55], v[50:51], off offset:1536
	ds_read_b128 v[50:53], v45 offset:12288
	ds_read_b128 v[56:59], v45 offset:4096
	v_pk_mul_f32 v[60:61], v[48:49], v[44:45] op_sel_hi:[1,0]
	v_pk_mul_f32 v[62:63], v[46:47], v[44:45] op_sel_hi:[1,0]
	ds_read_b128 v[46:49], v45 offset:13312
	s_waitcnt lgkmcnt(2)
	v_pk_add_f32 v[84:85], v[52:53], 1.0 op_sel_hi:[1,0]
	v_pk_add_f32 v[86:87], v[50:51], 1.0 op_sel_hi:[1,0]
	ds_read_b128 v[50:53], v45 offset:5120
	v_pk_mul_f32 v[40:41], v[40:41], v[44:45] op_sel_hi:[1,0]
	s_waitcnt lgkmcnt(1)
	v_pk_add_f32 v[46:47], v[46:47], 1.0 op_sel_hi:[1,0]
	v_pk_fma_f32 v[56:57], v[86:87], v[60:61], v[56:57]
	v_pk_mul_f32 v[42:43], v[42:43], v[44:45] op_sel_hi:[1,0]
	s_waitcnt lgkmcnt(0)
	v_pk_fma_f32 v[40:41], v[46:47], v[40:41], v[50:51]
	v_pk_add_f32 v[48:49], v[48:49], 1.0 op_sel_hi:[1,0]
	v_pk_fma_f32 v[58:59], v[84:85], v[62:63], v[58:59]
	v_pk_fma_f32 v[42:43], v[48:49], v[42:43], v[52:53]
	v_cvt_pk_bf16_f32 v56, v56, v57
	v_cvt_pk_bf16_f32 v40, v40, v41
	v_cvt_pk_bf16_f32 v57, v58, v59
	v_cvt_pk_bf16_f32 v41, v42, v43
	global_store_dwordx2 v[54:55], v[56:57], off offset:2048
	global_store_dwordx2 v[54:55], v[40:41], off offset:2560
	ds_read_b128 v[40:43], v45 offset:14336
	ds_read_b128 v[46:49], v45 offset:6144
	v_pk_mul_f32 v[50:51], v[36:37], v[44:45] op_sel_hi:[1,0]
	v_pk_mul_f32 v[52:53], v[38:39], v[44:45] op_sel_hi:[1,0]
	ds_read_b128 v[36:39], v45 offset:15360
	s_waitcnt lgkmcnt(2)
	v_pk_add_f32 v[58:59], v[40:41], 1.0 op_sel_hi:[1,0]
	v_pk_add_f32 v[56:57], v[42:43], 1.0 op_sel_hi:[1,0]
	s_waitcnt lgkmcnt(1)
	v_pk_fma_f32 v[46:47], v[58:59], v[50:51], v[46:47]
	ds_read_b128 v[40:43], v45 offset:7168
	v_pk_fma_f32 v[48:49], v[56:57], v[52:53], v[48:49]
	v_cvt_pk_bf16_f32 v46, v46, v47
	v_bfe_u32 v45, v48, 16, 1
	v_add3_u32 v45, v48, v45, s28
	v_lshrrev_b32_e32 v45, 16, v45
	v_pk_mul_f32 v[34:35], v[34:35], v[44:45] op_sel_hi:[1,0]
	s_waitcnt lgkmcnt(1)
	v_pk_add_f32 v[36:37], v[36:37], 1.0 op_sel_hi:[1,0]
	v_pk_mul_f32 v[32:33], v[32:33], v[44:45] op_sel_hi:[1,0]
	s_waitcnt lgkmcnt(0)
	v_pk_fma_f32 v[34:35], v[36:37], v[34:35], v[40:41]
	v_pk_add_f32 v[38:39], v[38:39], 1.0 op_sel_hi:[1,0]
	v_pk_fma_f32 v[32:33], v[38:39], v[32:33], v[42:43]
	v_cvt_pk_bf16_f32 v34, v34, v35
	v_bfe_u32 v47, v49, 16, 1
	v_add3_u32 v47, v49, v47, s28
	v_and_or_b32 v47, v47, s29, v45
	v_cvt_pk_bf16_f32 v35, v32, v33
	global_store_dwordx2 v[54:55], v[46:47], off offset:3072
	global_store_dwordx2 v[54:55], v[34:35], off offset:3584
	s_branch .LBB0_197

.LBB0_921:
	s_waitcnt vmcnt(15)
	v_cvt_f32_f16_sdwa v181, v166 dst_sel:DWORD dst_unused:UNUSED_PAD src0_sel:WORD_1
	v_cvt_f32_f16_e32 v180, v166
	s_waitcnt vmcnt(14)
	v_lshlrev_b32_e32 v178, 16, v168
	v_and_b32_e32 v179, 0xffff0000, v168
	v_lshlrev_b32_e32 v168, 16, v169
	v_and_b32_e32 v169, 0xffff0000, v169
	v_cvt_f32_f16_sdwa v183, v167 dst_sel:DWORD dst_unused:UNUSED_PAD src0_sel:WORD_1
	v_cvt_f32_f16_e32 v182, v167
	s_waitcnt lgkmcnt(7)
	v_pk_mul_f32 v[166:167], v[124:125], v[178:179]
	v_pk_mul_f32 v[124:125], v[126:127], v[168:169]
	s_waitcnt vmcnt(10)
	v_cvt_f32_f16_sdwa v169, v164 dst_sel:DWORD dst_unused:UNUSED_PAD src0_sel:WORD_1
	v_cvt_f32_f16_e32 v168, v164
	v_pk_fma_f32 v[126:127], v[180:181], s[30:31], v[166:167] op_sel_hi:[1,0,1]
	v_lshlrev_b32_e32 v166, 16, v162
	v_and_b32_e32 v167, 0xffff0000, v162
	v_lshlrev_b32_e32 v162, 16, v163
	v_and_b32_e32 v163, 0xffff0000, v163
	v_cvt_f32_f16_sdwa v179, v165 dst_sel:DWORD dst_unused:UNUSED_PAD src0_sel:WORD_1
	v_cvt_f32_f16_e32 v178, v165
	s_waitcnt lgkmcnt(6)
	v_pk_mul_f32 v[164:165], v[120:121], v[166:167]
	v_pk_mul_f32 v[120:121], v[122:123], v[162:163]
	v_pk_fma_f32 v[122:123], v[168:169], s[30:31], v[164:165] op_sel_hi:[1,0,1]
	s_waitcnt vmcnt(9)
	v_cvt_f32_f16_sdwa v165, v160 dst_sel:DWORD dst_unused:UNUSED_PAD src0_sel:WORD_1
	v_cvt_f32_f16_e32 v164, v160
	v_lshlrev_b32_e32 v162, 16, v158
	v_and_b32_e32 v163, 0xffff0000, v158
	v_lshlrev_b32_e32 v158, 16, v159
	v_and_b32_e32 v159, 0xffff0000, v159
	v_cvt_f32_f16_sdwa v167, v161 dst_sel:DWORD dst_unused:UNUSED_PAD src0_sel:WORD_1
	v_cvt_f32_f16_e32 v166, v161
	s_waitcnt lgkmcnt(5)
	v_pk_mul_f32 v[160:161], v[116:117], v[162:163]
	v_pk_mul_f32 v[116:117], v[118:119], v[158:159]
	v_pk_fma_f32 v[118:119], v[164:165], s[30:31], v[160:161] op_sel_hi:[1,0,1]
	s_waitcnt vmcnt(8)
	v_cvt_f32_f16_sdwa v161, v154 dst_sel:DWORD dst_unused:UNUSED_PAD src0_sel:WORD_1
	v_cvt_f32_f16_e32 v160, v154
	v_lshlrev_b32_e32 v158, 16, v156
	v_and_b32_e32 v159, 0xffff0000, v156
	v_lshlrev_b32_e32 v156, 16, v157
	v_and_b32_e32 v157, 0xffff0000, v157
	v_cvt_f32_f16_sdwa v163, v155 dst_sel:DWORD dst_unused:UNUSED_PAD src0_sel:WORD_1
	v_cvt_f32_f16_e32 v162, v155
	s_waitcnt lgkmcnt(4)
	v_pk_mul_f32 v[154:155], v[112:113], v[158:159]
	v_pk_mul_f32 v[112:113], v[114:115], v[156:157]
	v_pk_fma_f32 v[114:115], v[160:161], s[30:31], v[154:155] op_sel_hi:[1,0,1]
	s_waitcnt vmcnt(6)
	v_lshlrev_b32_e32 v154, 16, v152
	v_and_b32_e32 v155, 0xffff0000, v152
	v_lshlrev_b32_e32 v152, 16, v153
	v_and_b32_e32 v153, 0xffff0000, v153
	s_waitcnt lgkmcnt(3)
	v_pk_mul_f32 v[110:111], v[110:111], v[152:153]
	s_waitcnt vmcnt(2)
	v_cvt_f32_f16_sdwa v153, v148 dst_sel:DWORD dst_unused:UNUSED_PAD src0_sel:WORD_1
	v_cvt_f32_f16_e32 v152, v148
	v_cvt_f32_f16_sdwa v157, v150 dst_sel:DWORD dst_unused:UNUSED_PAD src0_sel:WORD_1
	v_cvt_f32_f16_sdwa v159, v151 dst_sel:DWORD dst_unused:UNUSED_PAD src0_sel:WORD_1
	v_cvt_f32_f16_e32 v158, v151
	v_cvt_f32_f16_e32 v156, v150
	v_lshlrev_b32_e32 v150, 16, v146
	v_and_b32_e32 v151, 0xffff0000, v146
	v_pk_mul_f32 v[108:109], v[108:109], v[154:155]
	v_lshlrev_b32_e32 v146, 16, v147
	v_and_b32_e32 v147, 0xffff0000, v147
	v_cvt_f32_f16_sdwa v155, v149 dst_sel:DWORD dst_unused:UNUSED_PAD src0_sel:WORD_1
	v_cvt_f32_f16_e32 v154, v149
	s_waitcnt lgkmcnt(2)
	v_pk_mul_f32 v[148:149], v[104:105], v[150:151]
	v_pk_mul_f32 v[104:105], v[106:107], v[146:147]
	v_pk_fma_f32 v[106:107], v[152:153], s[30:31], v[148:149] op_sel_hi:[1,0,1]
	s_waitcnt vmcnt(1)
	v_cvt_f32_f16_sdwa v149, v142 dst_sel:DWORD dst_unused:UNUSED_PAD src0_sel:WORD_1
	v_cvt_f32_f16_e32 v148, v142
	v_lshlrev_b32_e32 v146, 16, v140
	v_and_b32_e32 v147, 0xffff0000, v140
	v_lshlrev_b32_e32 v140, 16, v141
	v_and_b32_e32 v141, 0xffff0000, v141
	v_cvt_f32_f16_sdwa v151, v143 dst_sel:DWORD dst_unused:UNUSED_PAD src0_sel:WORD_1
	v_cvt_f32_f16_e32 v150, v143
	s_waitcnt lgkmcnt(1)
	v_pk_mul_f32 v[142:143], v[100:101], v[146:147]
	v_pk_mul_f32 v[100:101], v[102:103], v[140:141]
	v_lshlrev_b32_e32 v140, 16, v138
	v_and_b32_e32 v141, 0xffff0000, v138
	v_lshlrev_b32_e32 v138, 16, v139
	v_and_b32_e32 v139, 0xffff0000, v139
	v_pk_fma_f32 v[124:125], v[182:183], s[30:31], v[124:125] op_sel_hi:[1,0,1]
	v_pk_fma_f32 v[120:121], v[178:179], s[30:31], v[120:121] op_sel_hi:[1,0,1]
	v_pk_fma_f32 v[102:103], v[148:149], s[30:31], v[142:143] op_sel_hi:[1,0,1]
	s_waitcnt vmcnt(0)
	v_cvt_f32_f16_sdwa v143, v136 dst_sel:DWORD dst_unused:UNUSED_PAD src0_sel:WORD_1
	v_cvt_f32_f16_sdwa v147, v137 dst_sel:DWORD dst_unused:UNUSED_PAD src0_sel:WORD_1
	v_cvt_f32_f16_e32 v146, v137
	v_cvt_f32_f16_e32 v142, v136
	s_waitcnt lgkmcnt(0)
	v_pk_mul_f32 v[98:99], v[98:99], v[138:139]
	v_mov_b32_e32 v136, v126
	v_mov_b32_e32 v137, v122
	v_mov_b32_e32 v138, v127
	v_mov_b32_e32 v139, v123
	v_pk_mul_f32 v[96:97], v[96:97], v[140:141]
	v_pk_add_f32 v[136:137], v[136:137], v[138:139]
	v_mov_b32_e32 v138, v124
	v_mov_b32_e32 v139, v120
	v_mov_b32_e32 v140, v125
	v_mov_b32_e32 v141, v121
	v_pk_fma_f32 v[116:117], v[166:167], s[30:31], v[116:117] op_sel_hi:[1,0,1]
	v_pk_add_f32 v[138:139], v[138:139], v[140:141]
	v_mov_b32_e32 v140, v118
	v_pk_add_f32 v[136:137], v[136:137], v[138:139]
	v_pk_mov_b32 v[138:139], v[118:119], v[116:117] op_sel:[1,0]
	v_mov_b32_e32 v141, v117
	v_pk_add_f32 v[138:139], v[138:139], v[140:141]
	v_pk_fma_f32 v[112:113], v[162:163], s[30:31], v[112:113] op_sel_hi:[1,0,1]
	v_pk_fma_f32 v[110:111], v[158:159], s[30:31], v[110:111] op_sel_hi:[1,0,1]
	v_pk_fma_f32 v[108:109], v[156:157], s[30:31], v[108:109] op_sel_hi:[1,0,1]
	v_add_f32_e32 v136, 0, v136
	v_pk_add_f32 v[138:139], v[138:139], v[138:139] op_sel:[0,1] op_sel_hi:[1,0]
	v_pk_fma_f32 v[96:97], v[142:143], s[30:31], v[96:97] op_sel_hi:[1,0,1]
	v_add_f32_e32 v136, v136, v137
	v_add_f32_e32 v140, v114, v115
	v_add_f32_e32 v142, v112, v113
	v_mov_b32_e32 v137, v108
	v_mov_b32_e32 v139, v109
	v_mov_b32_e32 v141, v110
	v_mov_b32_e32 v143, v111
	v_pk_fma_f32 v[104:105], v[154:155], s[30:31], v[104:105] op_sel_hi:[1,0,1]
	v_pk_add_f32 v[136:137], v[136:137], v[138:139]
	v_pk_add_f32 v[138:139], v[140:141], v[142:143]
	v_mov_b32_e32 v140, v106
	v_pk_add_f32 v[136:137], v[136:137], v[138:139]
	v_pk_mov_b32 v[138:139], v[106:107], v[104:105] op_sel:[1,0]
	v_mov_b32_e32 v141, v105
	v_pk_add_f32 v[138:139], v[138:139], v[140:141]
	v_pk_fma_f32 v[100:101], v[150:151], s[30:31], v[100:101] op_sel_hi:[1,0,1]
	v_pk_fma_f32 v[98:99], v[146:147], s[30:31], v[98:99] op_sel_hi:[1,0,1]
	v_pk_add_f32 v[136:137], v[136:137], v[136:137] op_sel:[0,1] op_sel_hi:[1,0]
	v_pk_add_f32 v[138:139], v[138:139], v[138:139] op_sel:[0,1] op_sel_hi:[1,0]
	v_add_f32_e32 v140, v102, v103
	v_add_f32_e32 v142, v100, v101
	v_mov_b32_e32 v137, v96
	v_mov_b32_e32 v139, v97
	v_mov_b32_e32 v141, v98
	v_mov_b32_e32 v143, v99
	v_pk_add_f32 v[136:137], v[136:137], v[138:139]
	v_pk_add_f32 v[138:139], v[140:141], v[142:143]
	v_lshl_add_u64 v[164:165], v[134:135], 0, s[24:25]
	v_pk_add_f32 v[136:137], v[136:137], v[138:139]
	v_lshl_add_u64 v[168:169], v[134:135], 0, s[28:29]
	v_add_f32_e32 v136, v136, v137
	s_waitcnt lgkmcnt(0)
	s_nop 1
	v_add_f32_dpp v136, v136, v136 quad_perm:[1,0,3,2] row_mask:0xf bank_mask:0xf
	s_nop 1
	v_add_f32_dpp v136, v136, v136 quad_perm:[2,3,0,1] row_mask:0xf bank_mask:0xf
	s_nop 1
	v_add_f32_dpp v136, v136, v136 row_half_mirror row_mask:0xf bank_mask:0xf
	s_nop 1
	v_add_f32_dpp v136, v136, v136 row_ror:8 row_mask:0xf bank_mask:0xf
	s_nop 0
	v_readlane_b32 s100, v136, 0
	v_readlane_b32 s101, v136, 16
	s_nop 0
	v_mov_b32_e32 v137, s100
	v_add_f32_e32 v137, s101, v137
	v_readlane_b32 s100, v136, 32
	v_readlane_b32 s101, v136, 48
	s_nop 0
	v_add_f32_e32 v137, s100, v137
	v_add_f32_e32 v146, s101, v137
	v_fmamk_f32 v127, v146, 0xba000000, v127
	v_fmamk_f32 v123, v146, 0xba000000, v123
	v_fmamk_f32 v125, v146, 0xba000000, v125
	v_fmac_f32_e32 v126, 0xba000000, v146
	v_fmamk_f32 v121, v146, 0xba000000, v121
	v_fmac_f32_e32 v122, 0xba000000, v146
	v_mov_b32_e32 v138, v127
	v_mov_b32_e32 v139, v123
	v_fmac_f32_e32 v124, 0xba000000, v146
	v_fmac_f32_e32 v120, 0xba000000, v146
	v_mov_b32_e32 v136, v126
	v_mov_b32_e32 v137, v122
	v_pk_mul_f32 v[138:139], v[138:139], v[138:139]
	v_mov_b32_e32 v140, v125
	v_mov_b32_e32 v141, v121
	v_pk_fma_f32 v[136:137], v[136:137], v[136:137], v[138:139]
	v_mov_b32_e32 v138, v124
	v_mov_b32_e32 v139, v120
	v_pk_mul_f32 v[140:141], v[140:141], v[140:141]
	v_fmamk_f32 v119, v146, 0xba000000, v119
	v_pk_fma_f32 v[138:139], v[138:139], v[138:139], v[140:141]
	v_fmac_f32_e32 v118, 0xba000000, v146
	v_pk_add_f32 v[136:137], v[136:137], v[138:139]
	v_fmamk_f32 v117, v146, 0xba000000, v117
	v_fmac_f32_e32 v116, 0xba000000, v146
	v_pk_add_f32 v[136:137], v[136:137], v[136:137] op_sel_hi:[0,1]
	v_pk_mul_f32 v[138:139], v[116:117], v[116:117]
	v_pk_mul_f32 v[140:141], v[118:119], v[118:119]
	v_fmac_f32_e32 v114, 0xba000000, v146
	v_pk_mov_b32 v[142:143], v[140:141], v[138:139] op_sel:[1,0]
	v_mov_b32_e32 v141, v139
	v_fmamk_f32 v115, v146, 0xba000000, v115
	v_fmac_f32_e32 v112, 0xba000000, v146
	v_mul_f32_e32 v136, v114, v114
	v_pk_add_f32 v[138:139], v[142:143], v[140:141]
	v_fmamk_f32 v113, v146, 0xba000000, v113
	v_pk_fma_f32 v[140:141], v[114:115], v[114:115], v[136:137] op_sel_hi:[1,1,0]
	v_mul_f32_e32 v136, v112, v112
	v_pk_add_f32 v[138:139], v[138:139], v[138:139] op_sel_hi:[0,1]
	v_pk_fma_f32 v[142:143], v[112:113], v[112:113], v[136:137] op_sel_hi:[1,1,0]
	v_fmamk_f32 v111, v146, 0xba000000, v111
	v_fmac_f32_e32 v110, 0xba000000, v146
	v_fmamk_f32 v109, v146, 0xba000000, v109
	v_fmac_f32_e32 v108, 0xba000000, v146
	v_mul_f32_e32 v140, v108, v108
	v_mul_f32_e32 v142, v109, v109
	v_mul_f32_e32 v138, v110, v110
	v_mul_f32_e32 v136, v111, v111
	v_pk_add_f32 v[140:141], v[140:141], v[142:143]
	v_pk_add_f32 v[136:137], v[138:139], v[136:137]
	v_fmamk_f32 v107, v146, 0xba000000, v107
	v_pk_add_f32 v[136:137], v[140:141], v[136:137]
	v_fmac_f32_e32 v106, 0xba000000, v146
	v_fmamk_f32 v105, v146, 0xba000000, v105
	v_fmac_f32_e32 v104, 0xba000000, v146
	v_pk_add_f32 v[136:137], v[136:137], v[136:137] op_sel_hi:[0,1]
	v_pk_mul_f32 v[138:139], v[104:105], v[104:105]
	v_pk_mul_f32 v[140:141], v[106:107], v[106:107]
	v_fmac_f32_e32 v102, 0xba000000, v146
	v_pk_mov_b32 v[142:143], v[140:141], v[138:139] op_sel:[1,0]
	v_mov_b32_e32 v141, v139
	v_fmamk_f32 v103, v146, 0xba000000, v103
	v_fmac_f32_e32 v100, 0xba000000, v146
	v_mul_f32_e32 v136, v102, v102
	v_pk_add_f32 v[138:139], v[142:143], v[140:141]
	v_fmamk_f32 v101, v146, 0xba000000, v101
	v_pk_fma_f32 v[140:141], v[102:103], v[102:103], v[136:137] op_sel_hi:[1,1,0]
	v_mul_f32_e32 v136, v100, v100
	v_pk_add_f32 v[138:139], v[138:139], v[138:139] op_sel_hi:[0,1]
	v_pk_fma_f32 v[142:143], v[100:101], v[100:101], v[136:137] op_sel_hi:[1,1,0]
	v_fmamk_f32 v99, v146, 0xba000000, v99
	v_fmac_f32_e32 v98, 0xba000000, v146
	v_fmamk_f32 v97, v146, 0xba000000, v97
	v_fmac_f32_e32 v96, 0xba000000, v146
	v_mul_f32_e32 v140, v96, v96
	v_mul_f32_e32 v142, v97, v97
	v_mul_f32_e32 v138, v98, v98
	v_mul_f32_e32 v136, v99, v99
	v_pk_add_f32 v[140:141], v[140:141], v[142:143]
	v_pk_add_f32 v[136:137], v[138:139], v[136:137]
	s_nop 0
	v_pk_add_f32 v[136:137], v[140:141], v[136:137]
	s_nop 0
	v_add_f32_e32 v136, v136, v137
	s_waitcnt lgkmcnt(0)
	s_nop 1
	v_add_f32_dpp v136, v136, v136 quad_perm:[1,0,3,2] row_mask:0xf bank_mask:0xf
	s_nop 1
	v_add_f32_dpp v136, v136, v136 quad_perm:[2,3,0,1] row_mask:0xf bank_mask:0xf
	s_nop 1
	v_add_f32_dpp v136, v136, v136 row_half_mirror row_mask:0xf bank_mask:0xf
	s_nop 1
	v_add_f32_dpp v136, v136, v136 row_ror:8 row_mask:0xf bank_mask:0xf
	s_nop 0
	v_readlane_b32 s100, v136, 0
	v_readlane_b32 s101, v136, 16
	s_nop 0
	v_mov_b32_e32 v137, s100
	v_add_f32_e32 v137, s101, v137
	v_readlane_b32 s100, v136, 32
	v_readlane_b32 s101, v136, 48
	s_nop 0
	v_add_f32_e32 v137, s100, v137
	v_add_f32_e32 v136, s101, v137
	v_fmamk_f32 v136, v136, 0x3a000000, v229
	v_mul_f32_e32 v137, 0x4f800000, v136
	v_cmp_gt_f32_e32 vcc, s5, v136
	s_nop 1
	v_cndmask_b32_e32 v136, v136, v137, vcc
	v_sqrt_f32_e32 v137, v136
	s_nop 0
	v_add_u32_e32 v138, -1, v137
	v_fma_f32 v139, -v138, v137, v136
	v_cmp_ge_f32_e64 s[6:7], 0, v139
	v_add_u32_e32 v139, 1, v137
	s_nop 0
	v_cndmask_b32_e64 v138, v137, v138, s[6:7]
	v_fma_f32 v137, -v139, v137, v136
	v_cmp_lt_f32_e64 s[6:7], 0, v137
	s_nop 1
	v_cndmask_b32_e64 v137, v138, v139, s[6:7]
	v_mul_f32_e32 v138, 0x37800000, v137
	v_cndmask_b32_e32 v137, v137, v138, vcc
	v_cmp_class_f32_e32 vcc, v136, v230
	s_nop 1
	v_cndmask_b32_e32 v136, v137, v136, vcc
	v_div_scale_f32 v137, s[6:7], v136, v136, 1.0
	v_rcp_f32_e32 v138, v137
	s_nop 0
	v_fma_f32 v139, -v137, v138, 1.0
	v_fmac_f32_e32 v138, v139, v138
	v_div_scale_f32 v139, vcc, 1.0, v136, 1.0
	v_mul_f32_e32 v140, v139, v138
	v_fma_f32 v141, -v137, v140, v139
	v_fmac_f32_e32 v140, v141, v138
	v_fma_f32 v137, -v137, v140, v139
	v_div_fmas_f32 v137, v137, v138, v140
	v_div_fixup_f32 v136, v137, v136, 1.0
	v_pk_mul_f32 v[138:139], v[124:125], v[136:137] op_sel_hi:[1,0]
	v_pk_mul_f32 v[124:125], v[126:127], v[136:137] op_sel_hi:[1,0]
	v_pk_fma_f32 v[126:127], v[2:3], v[138:139], v[10:11]
	v_pk_mul_f32 v[138:139], v[120:121], v[136:137] op_sel_hi:[1,0]
	v_pk_mul_f32 v[120:121], v[122:123], v[136:137] op_sel_hi:[1,0]
	v_pk_fma_f32 v[122:123], v[6:7], v[138:139], v[14:15]
	v_pk_mul_f32 v[138:139], v[116:117], v[136:137] op_sel_hi:[1,0]
	v_pk_mul_f32 v[116:117], v[118:119], v[136:137] op_sel_hi:[1,0]
	v_pk_fma_f32 v[118:119], v[18:19], v[138:139], v[26:27]
	v_pk_mul_f32 v[138:139], v[112:113], v[136:137] op_sel_hi:[1,0]
	v_pk_mul_f32 v[112:113], v[114:115], v[136:137] op_sel_hi:[1,0]
	v_pk_fma_f32 v[114:115], v[22:23], v[138:139], v[30:31]
	v_pk_mul_f32 v[138:139], v[104:105], v[136:137] op_sel_hi:[1,0]
	v_pk_fma_f32 v[124:125], v[0:1], v[124:125], v[8:9]
	v_pk_fma_f32 v[120:121], v[4:5], v[120:121], v[12:13]
	v_pk_mul_f32 v[104:105], v[106:107], v[136:137] op_sel_hi:[1,0]
	v_pk_fma_f32 v[106:107], v[38:39], v[138:139], v[46:47]
	v_pk_mul_f32 v[138:139], v[100:101], v[136:137] op_sel_hi:[1,0]
	v_pk_mul_f32 v[110:111], v[110:111], v[136:137] op_sel_hi:[1,0]
	v_pk_mul_f32 v[108:109], v[108:109], v[136:137] op_sel_hi:[1,0]
	v_pk_mul_f32 v[100:101], v[102:103], v[136:137] op_sel_hi:[1,0]
	v_pk_fma_f32 v[102:103], v[50:51], v[138:139], v[58:59]
	v_pk_mul_f32 v[98:99], v[98:99], v[136:137] op_sel_hi:[1,0]
	v_pk_mul_f32 v[96:97], v[96:97], v[136:137] op_sel_hi:[1,0]
	v_mov_b32_e32 v136, v120
	v_mov_b32_e32 v137, v124
	v_mov_b32_e32 v138, v121
	v_mov_b32_e32 v139, v125
	v_pk_add_f32 v[136:137], v[136:137], v[138:139]
	v_mov_b32_e32 v138, v122
	v_mov_b32_e32 v139, v126
	v_mov_b32_e32 v140, v123
	v_mov_b32_e32 v141, v127
	v_pk_fma_f32 v[116:117], v[16:17], v[116:117], v[24:25]
	v_pk_add_f32 v[138:139], v[138:139], v[140:141]
	v_mov_b32_e32 v140, v116
	v_pk_add_f32 v[136:137], v[136:137], v[138:139]
	v_pk_mov_b32 v[138:139], v[116:117], v[118:119] op_sel:[1,0]
	v_mov_b32_e32 v141, v119
	v_pk_add_f32 v[138:139], v[138:139], v[140:141]
	v_pk_fma_f32 v[112:113], v[20:21], v[112:113], v[28:29]
	v_pk_fma_f32 v[108:109], v[32:33], v[108:109], v[40:41]
	v_pk_fma_f32 v[110:111], v[34:35], v[110:111], v[42:43]
	v_add_f32_e32 v137, 0, v137
	v_pk_add_f32 v[138:139], v[138:139], v[138:139] op_sel_hi:[0,1]
	v_add_f32_e32 v137, v136, v137
	v_add_f32_e32 v141, v112, v113
	v_add_f32_e32 v143, v114, v115
	v_mov_b32_e32 v140, v108
	v_mov_b32_e32 v142, v109
	v_mov_b32_e32 v138, v110
	v_mov_b32_e32 v136, v111
	v_pk_fma_f32 v[104:105], v[36:37], v[104:105], v[44:45]
	v_pk_add_f32 v[140:141], v[140:141], v[142:143]
	v_pk_add_f32 v[136:137], v[138:139], v[136:137]
	v_pk_mov_b32 v[138:139], v[104:105], v[106:107] op_sel:[1,0]
	v_pk_add_f32 v[136:137], v[140:141], v[136:137]
	v_mov_b32_e32 v140, v104
	v_mov_b32_e32 v141, v107
	v_pk_add_f32 v[138:139], v[138:139], v[140:141]
	v_pk_fma_f32 v[100:101], v[48:49], v[100:101], v[56:57]
	v_pk_fma_f32 v[96:97], v[52:53], v[96:97], v[60:61]
	v_pk_fma_f32 v[98:99], v[54:55], v[98:99], v[62:63]
	v_pk_add_f32 v[136:137], v[136:137], v[136:137] op_sel_hi:[0,1]
	v_pk_add_f32 v[138:139], v[138:139], v[138:139] op_sel_hi:[0,1]
	v_add_f32_e32 v141, v100, v101
	v_add_f32_e32 v143, v102, v103
	v_mov_b32_e32 v140, v96
	v_mov_b32_e32 v142, v97
	v_mov_b32_e32 v138, v98
	v_mov_b32_e32 v136, v99
	v_pk_add_f32 v[140:141], v[140:141], v[142:143]
	v_pk_add_f32 v[136:137], v[138:139], v[136:137]
	v_cvt_pk_f16_f32 v138, v120, v121
	v_pk_add_f32 v[136:137], v[140:141], v[136:137]
	v_cvt_pk_f16_f32 v139, v122, v123
	v_add_f32_e32 v136, v136, v137
	s_waitcnt lgkmcnt(0)
	s_nop 1
	v_add_f32_dpp v136, v136, v136 quad_perm:[1,0,3,2] row_mask:0xf bank_mask:0xf
	s_nop 1
	v_add_f32_dpp v136, v136, v136 quad_perm:[2,3,0,1] row_mask:0xf bank_mask:0xf
	s_nop 1
	v_add_f32_dpp v136, v136, v136 row_half_mirror row_mask:0xf bank_mask:0xf
	s_nop 1
	v_add_f32_dpp v136, v136, v136 row_ror:8 row_mask:0xf bank_mask:0xf
	s_nop 0
	v_readlane_b32 s100, v136, 0
	v_readlane_b32 s101, v136, 16
	s_nop 0
	v_mov_b32_e32 v137, s100
	v_add_f32_e32 v137, s101, v137
	v_readlane_b32 s100, v136, 32
	v_readlane_b32 s101, v136, 48
	s_nop 0
	v_add_f32_e32 v137, s100, v137
	v_add_f32_e32 v162, s101, v137
	v_cvt_pk_f16_f32 v142, v112, v113
	v_cvt_pk_f16_f32 v143, v114, v115
	v_cvt_pk_f16_f32 v149, v106, v107
	v_cvt_pk_f16_f32 v148, v104, v105
	v_cvt_pk_f16_f32 v153, v98, v99
	v_cvt_pk_f16_f32 v152, v96, v97
	v_cvt_pk_f16_f32 v136, v124, v125
	v_cvt_pk_f16_f32 v137, v126, v127
	v_cvt_pk_f16_f32 v141, v118, v119
	v_cvt_pk_f16_f32 v140, v116, v117
	v_cvt_pk_f16_f32 v147, v110, v111
	v_cvt_pk_f16_f32 v146, v108, v109
	v_cvt_pk_f16_f32 v150, v100, v101
	v_cvt_pk_f16_f32 v151, v102, v103
	v_fmamk_f32 v125, v162, 0xba000000, v125
	v_fmamk_f32 v121, v162, 0xba000000, v121
	v_fmamk_f32 v127, v162, 0xba000000, v127
	v_fmac_f32_e32 v124, 0xba000000, v162
	v_fmamk_f32 v123, v162, 0xba000000, v123
	v_fmac_f32_e32 v120, 0xba000000, v162
	v_mov_b32_e32 v156, v125
	v_mov_b32_e32 v157, v121
	v_fmac_f32_e32 v126, 0xba000000, v162
	v_fmac_f32_e32 v122, 0xba000000, v162
	v_mov_b32_e32 v154, v124
	v_mov_b32_e32 v155, v120
	v_pk_mul_f32 v[156:157], v[156:157], v[156:157]
	v_mov_b32_e32 v158, v127
	v_mov_b32_e32 v159, v123
	v_pk_fma_f32 v[154:155], v[154:155], v[154:155], v[156:157]
	v_mov_b32_e32 v156, v126
	v_mov_b32_e32 v157, v122
	v_pk_mul_f32 v[158:159], v[158:159], v[158:159]
	v_fmamk_f32 v117, v162, 0xba000000, v117
	v_pk_fma_f32 v[156:157], v[156:157], v[156:157], v[158:159]
	v_fmac_f32_e32 v116, 0xba000000, v162
	v_pk_add_f32 v[154:155], v[154:155], v[156:157]
	v_fmamk_f32 v119, v162, 0xba000000, v119
	v_fmac_f32_e32 v118, 0xba000000, v162
	v_pk_add_f32 v[154:155], v[154:155], v[154:155] op_sel_hi:[0,1]
	v_pk_mul_f32 v[156:157], v[118:119], v[118:119]
	v_pk_mul_f32 v[158:159], v[116:117], v[116:117]
	v_fmac_f32_e32 v112, 0xba000000, v162
	v_pk_mov_b32 v[160:161], v[158:159], v[156:157] op_sel:[1,0]
	v_mov_b32_e32 v159, v157
	v_fmamk_f32 v113, v162, 0xba000000, v113
	v_fmac_f32_e32 v114, 0xba000000, v162
	v_mul_f32_e32 v154, v112, v112
	v_pk_add_f32 v[156:157], v[160:161], v[158:159]
	v_fmamk_f32 v115, v162, 0xba000000, v115
	v_pk_fma_f32 v[158:159], v[112:113], v[112:113], v[154:155] op_sel_hi:[1,1,0]
	v_mul_f32_e32 v154, v114, v114
	v_pk_add_f32 v[156:157], v[156:157], v[156:157] op_sel_hi:[0,1]
	v_pk_fma_f32 v[160:161], v[114:115], v[114:115], v[154:155] op_sel_hi:[1,1,0]
	v_fmamk_f32 v111, v162, 0xba000000, v111
	v_fmac_f32_e32 v110, 0xba000000, v162
	v_fmamk_f32 v109, v162, 0xba000000, v109
	v_fmac_f32_e32 v108, 0xba000000, v162
	v_mul_f32_e32 v158, v108, v108
	v_mul_f32_e32 v160, v109, v109
	v_mul_f32_e32 v156, v110, v110
	v_mul_f32_e32 v154, v111, v111
	v_pk_add_f32 v[158:159], v[158:159], v[160:161]
	v_pk_add_f32 v[154:155], v[156:157], v[154:155]
	v_fmamk_f32 v105, v162, 0xba000000, v105
	v_pk_add_f32 v[154:155], v[158:159], v[154:155]
	v_fmac_f32_e32 v104, 0xba000000, v162
	v_fmamk_f32 v107, v162, 0xba000000, v107
	v_fmac_f32_e32 v106, 0xba000000, v162
	v_pk_add_f32 v[154:155], v[154:155], v[154:155] op_sel_hi:[0,1]
	v_pk_mul_f32 v[156:157], v[106:107], v[106:107]
	v_pk_mul_f32 v[158:159], v[104:105], v[104:105]
	v_fmac_f32_e32 v100, 0xba000000, v162
	v_pk_mov_b32 v[160:161], v[158:159], v[156:157] op_sel:[1,0]
	v_mov_b32_e32 v159, v157
	v_fmamk_f32 v101, v162, 0xba000000, v101
	v_fmac_f32_e32 v102, 0xba000000, v162
	v_mul_f32_e32 v154, v100, v100
	v_pk_add_f32 v[156:157], v[160:161], v[158:159]
	v_fmamk_f32 v103, v162, 0xba000000, v103
	v_pk_fma_f32 v[158:159], v[100:101], v[100:101], v[154:155] op_sel_hi:[1,1,0]
	v_mul_f32_e32 v154, v102, v102
	v_pk_add_f32 v[156:157], v[156:157], v[156:157] op_sel_hi:[0,1]
	v_pk_fma_f32 v[160:161], v[102:103], v[102:103], v[154:155] op_sel_hi:[1,1,0]
	v_fmamk_f32 v99, v162, 0xba000000, v99
	v_fmac_f32_e32 v98, 0xba000000, v162
	v_fmamk_f32 v97, v162, 0xba000000, v97
	v_fmac_f32_e32 v96, 0xba000000, v162
	v_mul_f32_e32 v158, v96, v96
	v_mul_f32_e32 v160, v97, v97
	v_mul_f32_e32 v156, v98, v98
	v_mul_f32_e32 v154, v99, v99
	v_pk_add_f32 v[158:159], v[158:159], v[160:161]
	v_pk_add_f32 v[154:155], v[156:157], v[154:155]
	v_lshl_add_u64 v[156:157], v[134:135], 0, s[10:11]
	v_pk_add_f32 v[154:155], v[158:159], v[154:155]
	v_lshl_add_u64 v[160:161], v[134:135], 0, s[20:21]
	v_add_f32_e32 v154, v154, v155
	ds_bpermute_b32 v155, v170, v154
	v_lshl_add_u64 v[162:163], v[134:135], 0, s[22:23]
	s_waitcnt lgkmcnt(0)
	v_add_f32_e32 v154, v154, v155
	ds_bpermute_b32 v155, v171, v154
	s_waitcnt lgkmcnt(0)
	v_add_f32_e32 v154, v154, v155
	ds_bpermute_b32 v155, v172, v154
	s_waitcnt lgkmcnt(0)
	v_add_f32_e32 v158, v154, v155
	ds_bpermute_b32 v159, v173, v158
	v_lshl_add_u64 v[154:155], v[134:135], 0, s[8:9]
	global_store_dwordx2 v[154:155], v[136:137], off
	global_store_dwordx2 v[156:157], v[138:139], off
	s_waitcnt lgkmcnt(0)
	v_add_f32_e32 v166, v158, v159
	ds_bpermute_b32 v167, v174, v166
	v_lshl_add_u64 v[158:159], v[134:135], 0, s[12:13]
	global_store_dwordx2 v[158:159], v[140:141], off
	global_store_dwordx2 v[160:161], v[142:143], off
	global_store_dwordx2 v[162:163], v[146:147], off
	s_waitcnt lgkmcnt(0)
	v_add_f32_e32 v177, v166, v167
	ds_bpermute_b32 v178, v175, v177
	v_lshl_add_u64 v[166:167], v[134:135], 0, s[26:27]
	global_store_dwordx2 v[164:165], v[148:149], off
	global_store_dwordx2 v[166:167], v[150:151], off
	global_store_dwordx2 v[168:169], v[152:153], off
	s_waitcnt lgkmcnt(0)
	v_add_f32_e32 v136, v177, v178
	v_fmamk_f32 v136, v136, 0x3a000000, v229
	v_mul_f32_e32 v137, 0x4f800000, v136
	v_cmp_gt_f32_e32 vcc, s5, v136
	s_nop 1
	v_cndmask_b32_e32 v136, v136, v137, vcc
	v_sqrt_f32_e32 v137, v136
	s_nop 0
	v_add_u32_e32 v138, -1, v137
	v_fma_f32 v139, -v138, v137, v136
	v_cmp_ge_f32_e64 s[6:7], 0, v139
	v_add_u32_e32 v139, 1, v137
	s_nop 0
	v_cndmask_b32_e64 v138, v137, v138, s[6:7]
	v_fma_f32 v137, -v139, v137, v136
	v_cmp_lt_f32_e64 s[6:7], 0, v137
	s_nop 1
	v_cndmask_b32_e64 v137, v138, v139, s[6:7]
	v_mul_f32_e32 v138, 0x37800000, v137
	v_cndmask_b32_e32 v137, v137, v138, vcc
	v_cmp_class_f32_e32 vcc, v136, v230
	s_nop 1
	v_cndmask_b32_e32 v136, v137, v136, vcc
	v_div_scale_f32 v137, s[6:7], v136, v136, 1.0
	v_rcp_f32_e32 v138, v137
	s_nop 0
	v_fma_f32 v139, -v137, v138, 1.0
	v_fmac_f32_e32 v138, v139, v138
	v_div_scale_f32 v139, vcc, 1.0, v136, 1.0
	v_mul_f32_e32 v140, v139, v138
	v_fma_f32 v141, -v137, v140, v139
	v_fmac_f32_e32 v140, v141, v138
	v_fma_f32 v137, -v137, v140, v139
	v_div_fmas_f32 v137, v137, v138, v140
	ds_read_b128 v[138:141], v144 offset:32768
	ds_read_b128 v[146:149], v144 offset:24576
	v_div_fixup_f32 v136, v137, v136, 1.0
	v_pk_mul_f32 v[142:143], v[124:125], v[136:137] op_sel_hi:[1,0]
	v_pk_mul_f32 v[150:151], v[126:127], v[136:137] op_sel_hi:[1,0]
	s_waitcnt lgkmcnt(1)
	v_pk_add_f32 v[154:155], v[138:139], 1.0 op_sel_hi:[1,0]
	ds_read_b128 v[124:127], v144 offset:33792
	s_waitcnt lgkmcnt(1)
	v_pk_fma_f32 v[142:143], v[154:155], v[142:143], v[146:147]
	v_pk_add_f32 v[152:153], v[140:141], 1.0 op_sel_hi:[1,0]
	ds_read_b128 v[138:141], v144 offset:25600
	v_pk_fma_f32 v[148:149], v[152:153], v[150:151], v[148:149]
	v_cvt_pk_bf16_f32 v142, v142, v143
	v_bfe_u32 v137, v148, 16, 1
	v_add3_u32 v137, v148, v137, s69
	v_lshrrev_b32_e32 v137, 16, v137
	v_pk_mul_f32 v[120:121], v[120:121], v[136:137] op_sel_hi:[1,0]
	s_waitcnt lgkmcnt(1)
	v_pk_add_f32 v[124:125], v[124:125], 1.0 op_sel_hi:[1,0]
	v_pk_mul_f32 v[122:123], v[122:123], v[136:137] op_sel_hi:[1,0]
	s_waitcnt lgkmcnt(0)
	v_pk_fma_f32 v[120:121], v[124:125], v[120:121], v[138:139]
	v_pk_add_f32 v[126:127], v[126:127], 1.0 op_sel_hi:[1,0]
	v_pk_fma_f32 v[122:123], v[126:127], v[122:123], v[140:141]
	v_cvt_pk_bf16_f32 v120, v120, v121
	v_bfe_u32 v143, v149, 16, 1
	v_add3_u32 v143, v149, v143, s69
	v_and_or_b32 v143, v143, s4, v137
	v_cvt_pk_bf16_f32 v121, v122, v123
	global_store_dwordx2 v[134:135], v[142:143], off
	global_store_dwordx2 v[134:135], v[120:121], off offset:512
	ds_read_b128 v[120:123], v144 offset:34816
	ds_read_b128 v[124:127], v144 offset:26624
	v_pk_mul_f32 v[138:139], v[116:117], v[136:137] op_sel_hi:[1,0]
	v_pk_mul_f32 v[140:141], v[118:119], v[136:137] op_sel_hi:[1,0]
	ds_read_b128 v[116:119], v144 offset:35840
	s_waitcnt lgkmcnt(2)
	v_pk_add_f32 v[142:143], v[122:123], 1.0 op_sel_hi:[1,0]
	v_pk_add_f32 v[146:147], v[120:121], 1.0 op_sel_hi:[1,0]
	ds_read_b128 v[120:123], v144 offset:27648
	s_waitcnt lgkmcnt(2)
	v_pk_fma_f32 v[124:125], v[146:147], v[138:139], v[124:125]
	s_waitcnt lgkmcnt(1)
	v_pk_add_f32 v[116:117], v[116:117], 1.0 op_sel_hi:[1,0]
	v_bfe_u32 v137, v124, 16, 1
	v_add3_u32 v124, v124, v137, s69
	v_bfe_u32 v137, v125, 16, 1
	v_pk_mul_f32 v[112:113], v[112:113], v[136:137] op_sel_hi:[1,0]
	v_pk_mul_f32 v[114:115], v[114:115], v[136:137] op_sel_hi:[1,0]
	s_waitcnt lgkmcnt(0)
	v_pk_fma_f32 v[112:113], v[116:117], v[112:113], v[120:121]
	v_pk_add_f32 v[118:119], v[118:119], 1.0 op_sel_hi:[1,0]
	v_pk_fma_f32 v[126:127], v[142:143], v[140:141], v[126:127]
	v_lshrrev_b32_e32 v124, 16, v124
	v_add3_u32 v125, v125, v137, s69
	v_pk_fma_f32 v[114:115], v[118:119], v[114:115], v[122:123]
	v_and_or_b32 v124, v125, s4, v124
	v_cvt_pk_bf16_f32 v112, v112, v113
	v_cvt_pk_bf16_f32 v125, v126, v127
	v_cvt_pk_bf16_f32 v113, v114, v115
	global_store_dwordx2 v[134:135], v[124:125], off offset:1024
	global_store_dwordx2 v[134:135], v[112:113], off offset:1536
	ds_read_b128 v[112:115], v144 offset:36864
	ds_read_b128 v[116:119], v144 offset:28672
	v_pk_mul_f32 v[120:121], v[108:109], v[136:137] op_sel_hi:[1,0]
	v_pk_mul_f32 v[122:123], v[110:111], v[136:137] op_sel_hi:[1,0]
	ds_read_b128 v[108:111], v144 offset:37888
	s_waitcnt lgkmcnt(2)
	v_pk_add_f32 v[124:125], v[114:115], 1.0 op_sel_hi:[1,0]
	v_pk_add_f32 v[126:127], v[112:113], 1.0 op_sel_hi:[1,0]
	ds_read_b128 v[112:115], v144 offset:29696
	v_pk_mul_f32 v[104:105], v[104:105], v[136:137] op_sel_hi:[1,0]
	s_waitcnt lgkmcnt(1)
	v_pk_add_f32 v[108:109], v[108:109], 1.0 op_sel_hi:[1,0]
	v_pk_fma_f32 v[116:117], v[126:127], v[120:121], v[116:117]
	v_pk_mul_f32 v[106:107], v[106:107], v[136:137] op_sel_hi:[1,0]
	s_waitcnt lgkmcnt(0)
	v_pk_fma_f32 v[104:105], v[108:109], v[104:105], v[112:113]
	v_pk_add_f32 v[110:111], v[110:111], 1.0 op_sel_hi:[1,0]
	v_pk_fma_f32 v[118:119], v[124:125], v[122:123], v[118:119]
	v_pk_fma_f32 v[106:107], v[110:111], v[106:107], v[114:115]
	v_cvt_pk_bf16_f32 v116, v116, v117
	v_cvt_pk_bf16_f32 v104, v104, v105
	v_cvt_pk_bf16_f32 v117, v118, v119
	v_cvt_pk_bf16_f32 v105, v106, v107
	global_store_dwordx2 v[134:135], v[116:117], off offset:2048
	global_store_dwordx2 v[134:135], v[104:105], off offset:2560
	ds_read_b128 v[104:107], v144 offset:38912
	ds_read_b128 v[108:111], v144 offset:30720
	v_pk_mul_f32 v[112:113], v[100:101], v[136:137] op_sel_hi:[1,0]
	v_pk_mul_f32 v[114:115], v[102:103], v[136:137] op_sel_hi:[1,0]
	ds_read_b128 v[100:103], v144 offset:39936
	s_waitcnt lgkmcnt(2)
	v_pk_add_f32 v[116:117], v[106:107], 1.0 op_sel_hi:[1,0]
	v_pk_add_f32 v[118:119], v[104:105], 1.0 op_sel_hi:[1,0]
	ds_read_b128 v[104:107], v144 offset:31744
	v_pk_mul_f32 v[96:97], v[96:97], v[136:137] op_sel_hi:[1,0]
	s_waitcnt lgkmcnt(1)
	v_pk_add_f32 v[100:101], v[100:101], 1.0 op_sel_hi:[1,0]
	v_pk_fma_f32 v[108:109], v[118:119], v[112:113], v[108:109]
	v_pk_mul_f32 v[98:99], v[98:99], v[136:137] op_sel_hi:[1,0]
	s_waitcnt lgkmcnt(0)
	v_pk_fma_f32 v[96:97], v[100:101], v[96:97], v[104:105]
	v_pk_add_f32 v[102:103], v[102:103], 1.0 op_sel_hi:[1,0]
	v_pk_fma_f32 v[110:111], v[116:117], v[114:115], v[110:111]
	v_pk_fma_f32 v[98:99], v[102:103], v[98:99], v[106:107]
	v_cvt_pk_bf16_f32 v108, v108, v109
	v_cvt_pk_bf16_f32 v96, v96, v97
	v_cvt_pk_bf16_f32 v109, v110, v111
	v_cvt_pk_bf16_f32 v97, v98, v99
	s_andn2_b64 vcc, exec, s[16:17]
	global_store_dwordx2 v[134:135], v[108:109], off offset:3072
	global_store_dwordx2 v[134:135], v[96:97], off offset:3584
	s_cbranch_vccnz .LBB0_918
	v_mov_b32_e32 v96, v68
	v_mov_b32_e32 v97, v64
	v_mov_b32_e32 v98, v69
	v_mov_b32_e32 v99, v65
	v_pk_add_f32 v[96:97], v[96:97], v[98:99]
	v_mov_b32_e32 v98, v70
	v_mov_b32_e32 v99, v66
	v_mov_b32_e32 v100, v71
	v_mov_b32_e32 v101, v67
	v_pk_add_f32 v[98:99], v[98:99], v[100:101]
	v_mov_b32_e32 v100, v72
	v_pk_add_f32 v[96:97], v[96:97], v[98:99]
	v_mov_b32_e32 v98, v73
	v_mov_b32_e32 v99, v74
	v_mov_b32_e32 v101, v75
	v_pk_add_f32 v[98:99], v[98:99], v[100:101]
	v_add_f32_e32 v97, 0, v97
	v_pk_add_f32 v[98:99], v[98:99], v[98:99] op_sel_hi:[0,1]
	v_add_f32_e32 v97, v96, v97
	v_add_f32_e32 v101, v76, v77
	v_add_f32_e32 v103, v78, v79
	v_mov_b32_e32 v100, v80
	v_mov_b32_e32 v102, v81
	v_mov_b32_e32 v98, v82
	v_mov_b32_e32 v96, v83
	v_pk_add_f32 v[100:101], v[100:101], v[102:103]
	v_pk_add_f32 v[96:97], v[98:99], v[96:97]
	v_mov_b32_e32 v98, v85
	v_pk_add_f32 v[96:97], v[100:101], v[96:97]
	v_mov_b32_e32 v99, v86
	v_mov_b32_e32 v100, v84
	v_mov_b32_e32 v101, v87
	v_pk_add_f32 v[98:99], v[98:99], v[100:101]
	v_pk_add_f32 v[96:97], v[96:97], v[96:97] op_sel_hi:[0,1]
	v_pk_add_f32 v[98:99], v[98:99], v[98:99] op_sel_hi:[0,1]
	v_add_f32_e32 v101, v88, v89
	v_add_f32_e32 v103, v90, v91
	v_mov_b32_e32 v100, v92
	v_mov_b32_e32 v102, v93
	v_mov_b32_e32 v98, v94
	v_mov_b32_e32 v96, v95
	v_pk_add_f32 v[100:101], v[100:101], v[102:103]
	v_pk_add_f32 v[96:97], v[98:99], v[96:97]
	s_ashr_i32 s15, s14, 31
	v_pk_add_f32 v[96:97], v[100:101], v[96:97]
	s_lshl_b64 s[16:17], s[14:15], 12
	v_add_f32_e32 v96, v96, v97
	ds_bpermute_b32 v97, v170, v96
	s_lshr_b32 s14, s14, 12
	s_mulk_i32 s14, 0x6000
	s_waitcnt lgkmcnt(0)
	v_add_f32_e32 v96, v96, v97
	ds_bpermute_b32 v97, v171, v96
	s_waitcnt lgkmcnt(0)
	v_add_f32_e32 v96, v96, v97
	ds_bpermute_b32 v97, v172, v96
	s_waitcnt lgkmcnt(0)
	v_add_f32_e32 v96, v96, v97
	ds_bpermute_b32 v97, v173, v96
	s_waitcnt lgkmcnt(0)
	v_add_f32_e32 v96, v96, v97
	ds_bpermute_b32 v97, v174, v96
	s_waitcnt lgkmcnt(0)
	v_add_f32_e32 v96, v96, v97
	ds_bpermute_b32 v97, v175, v96
	s_waitcnt lgkmcnt(0)
	v_add_f32_e32 v104, v96, v97
	v_fmamk_f32 v65, v104, 0xba000000, v65
	v_fmamk_f32 v69, v104, 0xba000000, v69
	v_fmamk_f32 v67, v104, 0xba000000, v67
	v_fmac_f32_e32 v64, 0xba000000, v104
	v_fmamk_f32 v71, v104, 0xba000000, v71
	v_fmac_f32_e32 v68, 0xba000000, v104
	v_mov_b32_e32 v98, v65
	v_mov_b32_e32 v99, v69
	v_fmamk_f32 v66, v104, 0xba000000, v66
	v_fmamk_f32 v70, v104, 0xba000000, v70
	v_mov_b32_e32 v96, v64
	v_mov_b32_e32 v97, v68
	v_pk_mul_f32 v[98:99], v[98:99], v[98:99]
	v_mov_b32_e32 v100, v67
	v_mov_b32_e32 v101, v71
	v_pk_fma_f32 v[96:97], v[96:97], v[96:97], v[98:99]
	v_mov_b32_e32 v98, v66
	v_mov_b32_e32 v99, v70
	v_pk_mul_f32 v[100:101], v[100:101], v[100:101]
	v_fmamk_f32 v73, v104, 0xba000000, v73
	v_pk_fma_f32 v[98:99], v[98:99], v[98:99], v[100:101]
	v_fmamk_f32 v72, v104, 0xba000000, v72
	v_pk_add_f32 v[96:97], v[96:97], v[98:99]
	v_fmamk_f32 v75, v104, 0xba000000, v75
	v_fmac_f32_e32 v74, 0xba000000, v104
	v_pk_add_f32 v[96:97], v[96:97], v[96:97] op_sel_hi:[0,1]
	v_pk_mul_f32 v[98:99], v[74:75], v[74:75]
	v_pk_mul_f32 v[100:101], v[72:73], v[72:73]
	v_fmamk_f32 v76, v104, 0xba000000, v76
	v_pk_mov_b32 v[102:103], v[100:101], v[98:99] op_sel:[1,0]
	v_mov_b32_e32 v101, v99
	v_fmamk_f32 v77, v104, 0xba000000, v77
	v_fmac_f32_e32 v78, 0xba000000, v104
	v_mul_f32_e32 v96, v76, v76
	v_pk_add_f32 v[98:99], v[102:103], v[100:101]
	v_fmamk_f32 v79, v104, 0xba000000, v79
	v_pk_fma_f32 v[100:101], v[76:77], v[76:77], v[96:97] op_sel_hi:[1,1,0]
	v_mul_f32_e32 v96, v78, v78
	v_pk_add_f32 v[98:99], v[98:99], v[98:99] op_sel_hi:[0,1]
	v_pk_fma_f32 v[102:103], v[78:79], v[78:79], v[96:97] op_sel_hi:[1,1,0]
	v_fmamk_f32 v83, v104, 0xba000000, v83
	v_fmamk_f32 v82, v104, 0xba000000, v82
	v_fmamk_f32 v81, v104, 0xba000000, v81
	v_fmac_f32_e32 v80, 0xba000000, v104
	v_mul_f32_e32 v100, v80, v80
	v_mul_f32_e32 v102, v81, v81
	v_mul_f32_e32 v98, v82, v82
	v_mul_f32_e32 v96, v83, v83
	v_pk_add_f32 v[100:101], v[100:101], v[102:103]
	v_pk_add_f32 v[96:97], v[98:99], v[96:97]
	v_fmamk_f32 v85, v104, 0xba000000, v85
	v_pk_add_f32 v[96:97], v[100:101], v[96:97]
	v_fmamk_f32 v84, v104, 0xba000000, v84
	v_fmamk_f32 v87, v104, 0xba000000, v87
	v_fmac_f32_e32 v86, 0xba000000, v104
	v_pk_add_f32 v[96:97], v[96:97], v[96:97] op_sel_hi:[0,1]
	v_pk_mul_f32 v[98:99], v[86:87], v[86:87]
	v_pk_mul_f32 v[100:101], v[84:85], v[84:85]
	v_fmamk_f32 v88, v104, 0xba000000, v88
	v_pk_mov_b32 v[102:103], v[100:101], v[98:99] op_sel:[1,0]
	v_mov_b32_e32 v101, v99
	v_fmamk_f32 v89, v104, 0xba000000, v89
	v_fmac_f32_e32 v90, 0xba000000, v104
	v_mul_f32_e32 v96, v88, v88
	v_pk_add_f32 v[98:99], v[102:103], v[100:101]
	v_fmamk_f32 v91, v104, 0xba000000, v91
	v_pk_fma_f32 v[100:101], v[88:89], v[88:89], v[96:97] op_sel_hi:[1,1,0]
	v_mul_f32_e32 v96, v90, v90
	v_pk_add_f32 v[98:99], v[98:99], v[98:99] op_sel_hi:[0,1]
	v_pk_fma_f32 v[102:103], v[90:91], v[90:91], v[96:97] op_sel_hi:[1,1,0]
	v_fmamk_f32 v95, v104, 0xba000000, v95
	v_fmamk_f32 v94, v104, 0xba000000, v94
	v_fmamk_f32 v93, v104, 0xba000000, v93
	v_fmac_f32_e32 v92, 0xba000000, v104
	v_mul_f32_e32 v100, v92, v92
	v_mul_f32_e32 v102, v93, v93
	v_mul_f32_e32 v98, v94, v94
	v_mul_f32_e32 v96, v95, v95
	v_pk_add_f32 v[100:101], v[100:101], v[102:103]
	v_pk_add_f32 v[96:97], v[98:99], v[96:97]
	s_nop 0
	v_pk_add_f32 v[96:97], v[100:101], v[96:97]
	s_nop 0
	v_add_f32_e32 v96, v96, v97
	s_waitcnt lgkmcnt(0)
	s_nop 1
	v_add_f32_dpp v96, v96, v96 quad_perm:[1,0,3,2] row_mask:0xf bank_mask:0xf
	s_nop 1
	v_add_f32_dpp v96, v96, v96 quad_perm:[2,3,0,1] row_mask:0xf bank_mask:0xf
	s_nop 1
	v_add_f32_dpp v96, v96, v96 row_half_mirror row_mask:0xf bank_mask:0xf
	s_nop 1
	v_add_f32_dpp v96, v96, v96 row_ror:8 row_mask:0xf bank_mask:0xf
	s_nop 0
	v_readlane_b32 s100, v96, 0
	v_readlane_b32 s101, v96, 16
	s_nop 0
	v_mov_b32_e32 v97, s100
	v_add_f32_e32 v97, s101, v97
	v_readlane_b32 s100, v96, 32
	v_readlane_b32 s101, v96, 48
	s_nop 0
	v_add_f32_e32 v97, s100, v97
	v_add_f32_e32 v96, s101, v97
	v_fmamk_f32 v96, v96, 0x3a000000, v229
	v_cmp_gt_f32_e32 vcc, s5, v96
	v_mul_f32_e32 v97, 0x4f800000, v96
	s_nop 0
	v_cndmask_b32_e32 v96, v96, v97, vcc
	v_sqrt_f32_e32 v97, v96
	s_nop 0
	v_add_u32_e32 v98, -1, v97
	v_fma_f32 v99, -v98, v97, v96
	v_cmp_ge_f32_e64 s[6:7], 0, v99
	v_add_u32_e32 v99, 1, v97
	s_nop 0
	v_cndmask_b32_e64 v98, v97, v98, s[6:7]
	v_fma_f32 v97, -v99, v97, v96
	v_cmp_lt_f32_e64 s[6:7], 0, v97
	s_nop 1
	v_cndmask_b32_e64 v97, v98, v99, s[6:7]
	v_mul_f32_e32 v98, 0x37800000, v97
	v_cndmask_b32_e32 v97, v97, v98, vcc
	v_cmp_class_f32_e32 vcc, v96, v230
	s_nop 1
	v_cndmask_b32_e32 v96, v97, v96, vcc
	v_div_scale_f32 v97, s[6:7], v96, v96, 1.0
	v_rcp_f32_e32 v98, v97
	s_nop 0
	v_fma_f32 v99, -v97, v98, 1.0
	v_fmac_f32_e32 v98, v99, v98
	v_div_scale_f32 v99, vcc, 1.0, v96, 1.0
	v_mul_f32_e32 v100, v99, v98
	v_fma_f32 v101, -v97, v100, v99
	v_fmac_f32_e32 v100, v101, v98
	v_fma_f32 v97, -v97, v100, v99
	v_div_fmas_f32 v97, v97, v98, v100
	v_div_fixup_f32 v96, v97, v96, 1.0
	v_pk_mul_f32 v[64:65], v[64:65], v[96:97] op_sel_hi:[1,0]
	v_pk_mul_f32 v[66:67], v[66:67], v[96:97] op_sel_hi:[1,0]
	v_pk_fma_f32 v[64:65], v[0:1], v[64:65], v[8:9]
	v_pk_fma_f32 v[66:67], v[2:3], v[66:67], v[10:11]
	v_pk_mul_f32 v[68:69], v[68:69], v[96:97] op_sel_hi:[1,0]
	v_pk_mul_f32 v[70:71], v[70:71], v[96:97] op_sel_hi:[1,0]
	v_cvt_pk_f16_f32 v99, v66, v67
	v_cvt_pk_f16_f32 v98, v64, v65
	v_lshl_add_u64 v[100:101], v[130:131], 0, s[16:17]
	v_pk_fma_f32 v[70:71], v[6:7], v[70:71], v[14:15]
	v_pk_fma_f32 v[68:69], v[4:5], v[68:69], v[12:13]
	v_pk_mul_f32 v[74:75], v[74:75], v[96:97] op_sel_hi:[1,0]
	v_pk_mul_f32 v[72:73], v[72:73], v[96:97] op_sel_hi:[1,0]
	global_store_dwordx2 v[100:101], v[98:99], off
	v_cvt_pk_f16_f32 v99, v70, v71
	v_cvt_pk_f16_f32 v98, v68, v69
	v_pk_fma_f32 v[72:73], v[16:17], v[72:73], v[24:25]
	v_pk_fma_f32 v[74:75], v[18:19], v[74:75], v[26:27]
	v_pk_mul_f32 v[78:79], v[78:79], v[96:97] op_sel_hi:[1,0]
	v_pk_mul_f32 v[76:77], v[76:77], v[96:97] op_sel_hi:[1,0]
	global_store_dwordx2 v[100:101], v[98:99], off offset:512
	v_cvt_pk_f16_f32 v99, v74, v75
	v_cvt_pk_f16_f32 v98, v72, v73
	v_pk_fma_f32 v[76:77], v[20:21], v[76:77], v[28:29]
	v_pk_fma_f32 v[78:79], v[22:23], v[78:79], v[30:31]
	v_pk_mul_f32 v[80:81], v[80:81], v[96:97] op_sel_hi:[1,0]
	v_pk_mul_f32 v[82:83], v[82:83], v[96:97] op_sel_hi:[1,0]
	global_store_dwordx2 v[100:101], v[98:99], off offset:1024
	v_cvt_pk_f16_f32 v99, v78, v79
	v_cvt_pk_f16_f32 v98, v76, v77
	v_pk_fma_f32 v[82:83], v[34:35], v[82:83], v[42:43]
	v_pk_fma_f32 v[80:81], v[32:33], v[80:81], v[40:41]
	v_pk_mul_f32 v[86:87], v[86:87], v[96:97] op_sel_hi:[1,0]
	v_pk_mul_f32 v[84:85], v[84:85], v[96:97] op_sel_hi:[1,0]
	global_store_dwordx2 v[100:101], v[98:99], off offset:1536
	v_cvt_pk_f16_f32 v99, v82, v83
	v_cvt_pk_f16_f32 v98, v80, v81
	v_pk_fma_f32 v[84:85], v[36:37], v[84:85], v[44:45]
	v_pk_fma_f32 v[86:87], v[38:39], v[86:87], v[46:47]
	v_pk_mul_f32 v[90:91], v[90:91], v[96:97] op_sel_hi:[1,0]
	v_pk_mul_f32 v[88:89], v[88:89], v[96:97] op_sel_hi:[1,0]
	v_pk_mul_f32 v[92:93], v[92:93], v[96:97] op_sel_hi:[1,0]
	v_pk_mul_f32 v[94:95], v[94:95], v[96:97] op_sel_hi:[1,0]
	global_store_dwordx2 v[100:101], v[98:99], off offset:2048
	v_cvt_pk_f16_f32 v99, v86, v87
	v_cvt_pk_f16_f32 v98, v84, v85
	v_pk_fma_f32 v[88:89], v[48:49], v[88:89], v[56:57]
	v_pk_fma_f32 v[90:91], v[50:51], v[90:91], v[58:59]
	v_pk_fma_f32 v[94:95], v[54:55], v[94:95], v[62:63]
	v_pk_fma_f32 v[92:93], v[52:53], v[92:93], v[60:61]
	global_store_dwordx2 v[100:101], v[98:99], off offset:2560
	v_cvt_pk_f16_f32 v99, v90, v91
	v_cvt_pk_f16_f32 v98, v88, v89
	v_cvt_pk_f16_f32 v97, v94, v95
	v_cvt_pk_f16_f32 v96, v92, v93
	global_store_dwordx2 v[100:101], v[98:99], off offset:3072
	global_store_dwordx2 v[100:101], v[96:97], off offset:3584
	v_mov_b32_e32 v96, v68
	v_mov_b32_e32 v97, v64
	v_mov_b32_e32 v98, v69
	v_mov_b32_e32 v99, v65
	v_pk_add_f32 v[96:97], v[96:97], v[98:99]
	v_mov_b32_e32 v98, v70
	v_mov_b32_e32 v99, v66
	v_mov_b32_e32 v100, v71
	v_mov_b32_e32 v101, v67
	v_pk_add_f32 v[98:99], v[98:99], v[100:101]
	v_mov_b32_e32 v100, v72
	v_pk_add_f32 v[96:97], v[96:97], v[98:99]
	v_pk_mov_b32 v[98:99], v[72:73], v[74:75] op_sel:[1,0]
	v_mov_b32_e32 v101, v75
	v_pk_add_f32 v[98:99], v[98:99], v[100:101]
	v_add_f32_e32 v97, 0, v97
	v_pk_add_f32 v[98:99], v[98:99], v[98:99] op_sel_hi:[0,1]
	v_add_f32_e32 v97, v96, v97
	v_add_f32_e32 v101, v76, v77
	v_add_f32_e32 v103, v78, v79
	v_mov_b32_e32 v100, v80
	v_mov_b32_e32 v102, v81
	v_mov_b32_e32 v98, v82
	v_mov_b32_e32 v96, v83
	v_pk_add_f32 v[100:101], v[100:101], v[102:103]
	v_pk_add_f32 v[96:97], v[98:99], v[96:97]
	v_pk_mov_b32 v[98:99], v[84:85], v[86:87] op_sel:[1,0]
	v_pk_add_f32 v[96:97], v[100:101], v[96:97]
	v_mov_b32_e32 v100, v84
	v_mov_b32_e32 v101, v87
	v_pk_add_f32 v[98:99], v[98:99], v[100:101]
	v_pk_add_f32 v[96:97], v[96:97], v[96:97] op_sel_hi:[0,1]
	v_pk_add_f32 v[98:99], v[98:99], v[98:99] op_sel_hi:[0,1]
	v_add_f32_e32 v101, v88, v89
	v_add_f32_e32 v103, v90, v91
	v_mov_b32_e32 v100, v92
	v_mov_b32_e32 v102, v93
	v_mov_b32_e32 v98, v94
	v_mov_b32_e32 v96, v95
	v_pk_add_f32 v[100:101], v[100:101], v[102:103]
	v_pk_add_f32 v[96:97], v[98:99], v[96:97]
	v_mov_b32_e32 v136, v64
	v_pk_add_f32 v[96:97], v[100:101], v[96:97]
	v_mov_b32_e32 v126, v68
	v_add_f32_e32 v96, v96, v97
	s_waitcnt lgkmcnt(0)
	s_nop 1
	v_add_f32_dpp v96, v96, v96 quad_perm:[1,0,3,2] row_mask:0xf bank_mask:0xf
	s_nop 1
	v_add_f32_dpp v96, v96, v96 quad_perm:[2,3,0,1] row_mask:0xf bank_mask:0xf
	s_nop 1
	v_add_f32_dpp v96, v96, v96 row_half_mirror row_mask:0xf bank_mask:0xf
	s_nop 1
	v_add_f32_dpp v96, v96, v96 row_ror:8 row_mask:0xf bank_mask:0xf
	s_nop 0
	v_readlane_b32 s100, v96, 0
	v_readlane_b32 s101, v96, 16
	s_nop 0
	v_mov_b32_e32 v97, s100
	v_add_f32_e32 v97, s101, v97
	v_readlane_b32 s100, v96, 32
	v_readlane_b32 s101, v96, 48
	s_nop 0
	v_add_f32_e32 v97, s100, v97
	v_add_f32_e32 v144, s101, v97
	v_mov_b32_e32 v110, v66
	v_mov_b32_e32 v124, v70
	v_mov_b32_e32 v120, v72
	v_mov_b32_e32 v122, v74
	v_mov_b32_e32 v116, v76
	v_mov_b32_e32 v118, v78
	v_mov_b32_e32 v112, v82
	v_mov_b32_e32 v114, v80
	v_mov_b32_e32 v104, v84
	v_mov_b32_e32 v106, v86
	v_fmamk_f32 v137, v144, 0xba000000, v65
	v_fmamk_f32 v127, v144, 0xba000000, v69
	v_fmamk_f32 v111, v144, 0xba000000, v67
	v_fmac_f32_e32 v136, 0xba000000, v144
	v_fmamk_f32 v125, v144, 0xba000000, v71
	v_fmac_f32_e32 v126, 0xba000000, v144
	v_mov_b32_e32 v98, v137
	v_mov_b32_e32 v99, v127
	v_fmac_f32_e32 v110, 0xba000000, v144
	v_fmac_f32_e32 v124, 0xba000000, v144
	v_mov_b32_e32 v96, v136
	v_mov_b32_e32 v97, v126
	v_pk_mul_f32 v[98:99], v[98:99], v[98:99]
	v_mov_b32_e32 v100, v111
	v_mov_b32_e32 v101, v125
	v_pk_fma_f32 v[96:97], v[96:97], v[96:97], v[98:99]
	v_mov_b32_e32 v98, v110
	v_mov_b32_e32 v99, v124
	v_pk_mul_f32 v[100:101], v[100:101], v[100:101]
	v_fmamk_f32 v121, v144, 0xba000000, v73
	v_pk_fma_f32 v[98:99], v[98:99], v[98:99], v[100:101]
	v_fmac_f32_e32 v120, 0xba000000, v144
	v_pk_add_f32 v[96:97], v[96:97], v[98:99]
	v_fmamk_f32 v123, v144, 0xba000000, v75
	v_fmac_f32_e32 v122, 0xba000000, v144
	v_pk_add_f32 v[96:97], v[96:97], v[96:97] op_sel_hi:[0,1]
	v_pk_mul_f32 v[98:99], v[122:123], v[122:123]
	v_pk_mul_f32 v[100:101], v[120:121], v[120:121]
	v_fmac_f32_e32 v116, 0xba000000, v144
	v_pk_mov_b32 v[102:103], v[100:101], v[98:99] op_sel:[1,0]
	v_mov_b32_e32 v101, v99
	v_fmamk_f32 v117, v144, 0xba000000, v77
	v_fmac_f32_e32 v118, 0xba000000, v144
	v_mul_f32_e32 v96, v116, v116
	v_pk_add_f32 v[98:99], v[102:103], v[100:101]
	v_fmamk_f32 v119, v144, 0xba000000, v79
	v_pk_fma_f32 v[100:101], v[116:117], v[116:117], v[96:97] op_sel_hi:[1,1,0]
	v_mul_f32_e32 v96, v118, v118
	v_pk_add_f32 v[98:99], v[98:99], v[98:99] op_sel_hi:[0,1]
	v_pk_fma_f32 v[102:103], v[118:119], v[118:119], v[96:97] op_sel_hi:[1,1,0]
	v_fmamk_f32 v113, v144, 0xba000000, v83
	v_fmac_f32_e32 v112, 0xba000000, v144
	v_fmamk_f32 v115, v144, 0xba000000, v81
	v_fmac_f32_e32 v114, 0xba000000, v144
	v_mul_f32_e32 v100, v114, v114
	v_mul_f32_e32 v102, v115, v115
	v_mul_f32_e32 v98, v112, v112
	v_mul_f32_e32 v96, v113, v113
	v_pk_add_f32 v[100:101], v[100:101], v[102:103]
	v_pk_add_f32 v[96:97], v[98:99], v[96:97]
	v_fmamk_f32 v105, v144, 0xba000000, v85
	v_pk_add_f32 v[96:97], v[100:101], v[96:97]
	v_fmac_f32_e32 v104, 0xba000000, v144
	v_fmamk_f32 v107, v144, 0xba000000, v87
	v_fmac_f32_e32 v106, 0xba000000, v144
	v_pk_add_f32 v[108:109], v[96:97], v[96:97] op_sel_hi:[0,1]
	v_pk_mul_f32 v[96:97], v[106:107], v[106:107]
	v_pk_mul_f32 v[98:99], v[104:105], v[104:105]
	v_mov_b32_e32 v102, v90
	v_pk_mov_b32 v[100:101], v[98:99], v[96:97] op_sel:[1,0]
	v_mov_b32_e32 v99, v97
	v_pk_add_f32 v[96:97], v[100:101], v[98:99]
	v_mov_b32_e32 v100, v88
	v_fmac_f32_e32 v100, 0xba000000, v144
	v_pk_add_f32 v[138:139], v[96:97], v[96:97] op_sel_hi:[0,1]
	v_fmamk_f32 v101, v144, 0xba000000, v89
	v_fmac_f32_e32 v102, 0xba000000, v144
	v_mul_f32_e32 v96, v100, v100
	v_fmamk_f32 v103, v144, 0xba000000, v91
	v_pk_fma_f32 v[140:141], v[100:101], v[100:101], v[96:97] op_sel_hi:[1,1,0]
	v_mul_f32_e32 v96, v102, v102
	v_pk_fma_f32 v[142:143], v[102:103], v[102:103], v[96:97] op_sel_hi:[1,1,0]
	v_mov_b32_e32 v96, v94
	v_mov_b32_e32 v98, v92
	v_fmamk_f32 v97, v144, 0xba000000, v95
	v_fmac_f32_e32 v96, 0xba000000, v144
	v_fmamk_f32 v99, v144, 0xba000000, v93
	v_fmac_f32_e32 v98, 0xba000000, v144
	v_mul_f32_e32 v140, v98, v98
	v_mul_f32_e32 v142, v99, v99
	v_mul_f32_e32 v138, v96, v96
	v_mul_f32_e32 v108, v97, v97
	v_pk_add_f32 v[140:141], v[140:141], v[142:143]
	v_pk_add_f32 v[108:109], v[138:139], v[108:109]
	s_nop 0
	v_pk_add_f32 v[108:109], v[140:141], v[108:109]
	s_nop 0
	v_add_f32_e32 v108, v108, v109
	s_waitcnt lgkmcnt(0)
	s_nop 1
	v_add_f32_dpp v108, v108, v108 quad_perm:[1,0,3,2] row_mask:0xf bank_mask:0xf
	s_nop 1
	v_add_f32_dpp v108, v108, v108 quad_perm:[2,3,0,1] row_mask:0xf bank_mask:0xf
	s_nop 1
	v_add_f32_dpp v108, v108, v108 row_half_mirror row_mask:0xf bank_mask:0xf
	s_nop 1
	v_add_f32_dpp v108, v108, v108 row_ror:8 row_mask:0xf bank_mask:0xf
	s_nop 0
	v_readlane_b32 s100, v108, 0
	v_readlane_b32 s101, v108, 16
	s_nop 0
	v_mov_b32_e32 v109, s100
	v_add_f32_e32 v109, s101, v109
	v_readlane_b32 s100, v108, 32
	v_readlane_b32 s101, v108, 48
	s_nop 0
	v_add_f32_e32 v109, s100, v109
	v_add_f32_e32 v108, s101, v109
	v_fmamk_f32 v108, v108, 0x3a000000, v229
	v_cmp_gt_f32_e32 vcc, s5, v108
	v_mul_f32_e32 v109, 0x4f800000, v108
	s_nop 0
	v_cndmask_b32_e32 v108, v108, v109, vcc
	v_sqrt_f32_e32 v109, v108
	s_nop 0
	v_add_u32_e32 v138, -1, v109
	v_fma_f32 v139, -v138, v109, v108
	v_cmp_ge_f32_e64 s[6:7], 0, v139
	v_add_u32_e32 v139, 1, v109
	s_nop 0
	v_cndmask_b32_e64 v138, v109, v138, s[6:7]
	v_fma_f32 v109, -v139, v109, v108
	v_cmp_lt_f32_e64 s[6:7], 0, v109
	s_nop 1
	v_cndmask_b32_e64 v109, v138, v139, s[6:7]
	v_mul_f32_e32 v138, 0x37800000, v109
	v_cndmask_b32_e32 v109, v109, v138, vcc
	v_cmp_class_f32_e32 vcc, v108, v230
	s_nop 1
	v_cndmask_b32_e32 v108, v109, v108, vcc
	v_div_scale_f32 v109, s[6:7], v108, v108, 1.0
	v_rcp_f32_e32 v138, v109
	s_nop 0
	v_fma_f32 v139, -v109, v138, 1.0
	v_fmac_f32_e32 v138, v139, v138
	v_div_scale_f32 v139, vcc, 1.0, v108, 1.0
	v_mul_f32_e32 v140, v139, v138
	v_fma_f32 v141, -v109, v140, v139
	v_fmac_f32_e32 v140, v141, v138
	v_fma_f32 v109, -v109, v140, v139
	v_div_fmas_f32 v109, v109, v138, v140
	v_div_fixup_f32 v108, v109, v108, 1.0
	v_add_u32_e32 v109, s14, v176
	ds_read_b128 v[138:141], v109 offset:24576
	ds_read_b128 v[146:149], v109 offset:32768
	v_pk_mul_f32 v[136:137], v[136:137], v[108:109] op_sel_hi:[1,0]
	v_pk_mul_f32 v[110:111], v[110:111], v[108:109] op_sel_hi:[1,0]
	v_pk_mul_f32 v[126:127], v[126:127], v[108:109] op_sel_hi:[1,0]
	v_pk_mul_f32 v[124:125], v[124:125], v[108:109] op_sel_hi:[1,0]
	s_waitcnt lgkmcnt(0)
	v_pk_add_f32 v[146:147], v[146:147], 1.0 op_sel_hi:[1,0]
	v_pk_add_f32 v[142:143], v[148:149], 1.0 op_sel_hi:[1,0]
	v_pk_fma_f32 v[136:137], v[146:147], v[136:137], v[138:139]
	v_pk_fma_f32 v[110:111], v[142:143], v[110:111], v[140:141]
	v_cvt_pk_bf16_f32 v136, v136, v137
	v_cvt_pk_bf16_f32 v137, v110, v111
	v_lshl_add_u64 v[110:111], v[132:133], 0, s[16:17]
	global_store_dwordx2 v[110:111], v[136:137], off
	ds_read_b128 v[136:139], v109 offset:25600
	ds_read_b128 v[140:143], v109 offset:33792
	v_pk_mul_f32 v[120:121], v[120:121], v[108:109] op_sel_hi:[1,0]
	v_pk_mul_f32 v[122:123], v[122:123], v[108:109] op_sel_hi:[1,0]
	v_pk_mul_f32 v[116:117], v[116:117], v[108:109] op_sel_hi:[1,0]
	v_pk_mul_f32 v[118:119], v[118:119], v[108:109] op_sel_hi:[1,0]
	s_waitcnt lgkmcnt(0)
	v_pk_add_f32 v[140:141], v[140:141], 1.0 op_sel_hi:[1,0]
	v_pk_add_f32 v[142:143], v[142:143], 1.0 op_sel_hi:[1,0]
	v_pk_fma_f32 v[126:127], v[140:141], v[126:127], v[136:137]
	v_pk_fma_f32 v[124:125], v[142:143], v[124:125], v[138:139]
	v_cvt_pk_bf16_f32 v126, v126, v127
	v_cvt_pk_bf16_f32 v127, v124, v125
	global_store_dwordx2 v[110:111], v[126:127], off offset:512
	ds_read_b128 v[124:127], v109 offset:26624
	ds_read_b128 v[136:139], v109 offset:34816
	v_pk_mul_f32 v[114:115], v[114:115], v[108:109] op_sel_hi:[1,0]
	v_pk_mul_f32 v[112:113], v[112:113], v[108:109] op_sel_hi:[1,0]
	v_pk_mul_f32 v[104:105], v[104:105], v[108:109] op_sel_hi:[1,0]
	v_pk_mul_f32 v[106:107], v[106:107], v[108:109] op_sel_hi:[1,0]
	s_waitcnt lgkmcnt(0)
	v_pk_add_f32 v[136:137], v[136:137], 1.0 op_sel_hi:[1,0]
	v_pk_add_f32 v[138:139], v[138:139], 1.0 op_sel_hi:[1,0]
	v_pk_fma_f32 v[120:121], v[136:137], v[120:121], v[124:125]
	v_pk_fma_f32 v[122:123], v[138:139], v[122:123], v[126:127]
	v_cvt_pk_bf16_f32 v120, v120, v121
	v_cvt_pk_bf16_f32 v121, v122, v123
	global_store_dwordx2 v[110:111], v[120:121], off offset:1024
	ds_read_b128 v[120:123], v109 offset:27648
	ds_read_b128 v[124:127], v109 offset:35840
	v_pk_mul_f32 v[100:101], v[100:101], v[108:109] op_sel_hi:[1,0]
	v_pk_mul_f32 v[102:103], v[102:103], v[108:109] op_sel_hi:[1,0]
	v_pk_mul_f32 v[98:99], v[98:99], v[108:109] op_sel_hi:[1,0]
	v_pk_mul_f32 v[96:97], v[96:97], v[108:109] op_sel_hi:[1,0]
	s_waitcnt lgkmcnt(0)
	v_pk_add_f32 v[124:125], v[124:125], 1.0 op_sel_hi:[1,0]
	v_pk_add_f32 v[126:127], v[126:127], 1.0 op_sel_hi:[1,0]
	v_pk_fma_f32 v[116:117], v[124:125], v[116:117], v[120:121]
	v_pk_fma_f32 v[118:119], v[126:127], v[118:119], v[122:123]
	v_cvt_pk_bf16_f32 v116, v116, v117
	v_cvt_pk_bf16_f32 v117, v118, v119
	global_store_dwordx2 v[110:111], v[116:117], off offset:1536
	ds_read_b128 v[116:119], v109 offset:28672
	ds_read_b128 v[120:123], v109 offset:36864
	s_waitcnt lgkmcnt(0)
	v_pk_add_f32 v[120:121], v[120:121], 1.0 op_sel_hi:[1,0]
	s_nop 0
	v_pk_fma_f32 v[114:115], v[120:121], v[114:115], v[116:117]
	v_pk_add_f32 v[122:123], v[122:123], 1.0 op_sel_hi:[1,0]
	v_pk_fma_f32 v[112:113], v[122:123], v[112:113], v[118:119]
	v_cvt_pk_bf16_f32 v114, v114, v115
	v_cvt_pk_bf16_f32 v115, v112, v113
	global_store_dwordx2 v[110:111], v[114:115], off offset:2048
	ds_read_b128 v[112:115], v109 offset:29696
	ds_read_b128 v[116:119], v109 offset:37888
	s_waitcnt lgkmcnt(0)
	v_pk_add_f32 v[116:117], v[116:117], 1.0 op_sel_hi:[1,0]
	s_nop 0
	v_pk_fma_f32 v[104:105], v[116:117], v[104:105], v[112:113]
	v_pk_add_f32 v[118:119], v[118:119], 1.0 op_sel_hi:[1,0]
	v_pk_fma_f32 v[106:107], v[118:119], v[106:107], v[114:115]
	v_cvt_pk_bf16_f32 v104, v104, v105
	v_cvt_pk_bf16_f32 v105, v106, v107
	global_store_dwordx2 v[110:111], v[104:105], off offset:2560
	ds_read_b128 v[104:107], v109 offset:30720
	ds_read_b128 v[112:115], v109 offset:38912
	s_waitcnt lgkmcnt(0)
	v_pk_add_f32 v[112:113], v[112:113], 1.0 op_sel_hi:[1,0]
	s_nop 0
	v_pk_fma_f32 v[100:101], v[112:113], v[100:101], v[104:105]
	v_pk_add_f32 v[114:115], v[114:115], 1.0 op_sel_hi:[1,0]
	v_pk_fma_f32 v[102:103], v[114:115], v[102:103], v[106:107]
	v_cvt_pk_bf16_f32 v100, v100, v101
	v_cvt_pk_bf16_f32 v101, v102, v103
	global_store_dwordx2 v[110:111], v[100:101], off offset:3072
	ds_read_b128 v[100:103], v109 offset:31744
	ds_read_b128 v[104:107], v109 offset:39936
	s_waitcnt lgkmcnt(0)
	v_pk_add_f32 v[104:105], v[104:105], 1.0 op_sel_hi:[1,0]
	s_nop 0
	v_pk_fma_f32 v[98:99], v[104:105], v[98:99], v[100:101]
	v_pk_add_f32 v[106:107], v[106:107], 1.0 op_sel_hi:[1,0]
	v_pk_fma_f32 v[96:97], v[106:107], v[96:97], v[102:103]
	v_cvt_pk_bf16_f32 v98, v98, v99
	v_cvt_pk_bf16_f32 v99, v96, v97
	global_store_dwordx2 v[110:111], v[98:99], off offset:3584
	s_branch .LBB0_918

.LBB0_1260:
	v_readlane_b32 s4, v254, 45
	v_readlane_b32 s5, v254, 46
	s_and_b64 vcc, exec, s[4:5]
	s_cbranch_vccz .LBB0_1262
	v_mov_b32_e32 v140, v116
	v_mov_b32_e32 v141, v124
	v_mov_b32_e32 v142, v117
	v_mov_b32_e32 v143, v125
	v_pk_add_f32 v[140:141], v[140:141], v[142:143]
	v_mov_b32_e32 v142, v118
	v_mov_b32_e32 v143, v126
	v_mov_b32_e32 v146, v119
	v_mov_b32_e32 v147, v127
	v_pk_add_f32 v[142:143], v[142:143], v[146:147]
	v_mov_b32_e32 v146, v120
	v_pk_add_f32 v[140:141], v[140:141], v[142:143]
	v_mov_b32_e32 v142, v121
	v_mov_b32_e32 v143, v122
	v_mov_b32_e32 v147, v123
	v_pk_add_f32 v[142:143], v[142:143], v[146:147]
	v_add_f32_e32 v141, 0, v141
	v_pk_add_f32 v[142:143], v[142:143], v[142:143] op_sel_hi:[0,1]
	v_add_f32_e32 v141, v140, v141
	v_add_f32_e32 v147, v108, v109
	v_add_f32_e32 v149, v110, v111
	v_mov_b32_e32 v146, v112
	v_mov_b32_e32 v148, v113
	v_mov_b32_e32 v142, v114
	v_mov_b32_e32 v140, v115
	v_pk_add_f32 v[146:147], v[146:147], v[148:149]
	v_pk_add_f32 v[140:141], v[142:143], v[140:141]
	v_mov_b32_e32 v142, v101
	v_pk_add_f32 v[140:141], v[146:147], v[140:141]
	v_mov_b32_e32 v143, v102
	v_mov_b32_e32 v146, v100
	v_mov_b32_e32 v147, v103
	v_pk_add_f32 v[142:143], v[142:143], v[146:147]
	v_pk_add_f32 v[140:141], v[140:141], v[140:141] op_sel_hi:[0,1]
	v_pk_add_f32 v[142:143], v[142:143], v[142:143] op_sel_hi:[0,1]
	v_add_f32_e32 v147, v104, v105
	v_add_f32_e32 v149, v106, v107
	v_mov_b32_e32 v146, v96
	v_mov_b32_e32 v148, v97
	v_mov_b32_e32 v142, v98
	v_mov_b32_e32 v140, v99
	v_pk_add_f32 v[146:147], v[146:147], v[148:149]
	v_pk_add_f32 v[140:141], v[142:143], v[140:141]
	s_mov_b32 s4, 0xf800000
	v_pk_add_f32 v[140:141], v[146:147], v[140:141]
	s_nop 0
	v_add_f32_e32 v140, v140, v141
	s_waitcnt lgkmcnt(0)
	s_nop 1
	v_add_f32_dpp v140, v140, v140 quad_perm:[1,0,3,2] row_mask:0xf bank_mask:0xf
	s_nop 1
	v_add_f32_dpp v140, v140, v140 quad_perm:[2,3,0,1] row_mask:0xf bank_mask:0xf
	s_nop 1
	v_add_f32_dpp v140, v140, v140 row_half_mirror row_mask:0xf bank_mask:0xf
	s_nop 1
	v_add_f32_dpp v140, v140, v140 row_ror:8 row_mask:0xf bank_mask:0xf
	s_nop 0
	v_readlane_b32 s100, v140, 0
	v_readlane_b32 s101, v140, 16
	s_nop 0
	v_mov_b32_e32 v141, s100
	v_add_f32_e32 v141, s101, v141
	v_readlane_b32 s100, v140, 32
	v_readlane_b32 s101, v140, 48
	s_nop 0
	v_add_f32_e32 v141, s100, v141
	v_add_f32_e32 v150, s101, v141
	v_fmamk_f32 v125, v150, 0xba000000, v125
	v_fmamk_f32 v117, v150, 0xba000000, v117
	v_fmamk_f32 v127, v150, 0xba000000, v127
	v_fmac_f32_e32 v124, 0xba000000, v150
	v_fmamk_f32 v119, v150, 0xba000000, v119
	v_fmac_f32_e32 v116, 0xba000000, v150
	v_mov_b32_e32 v142, v125
	v_mov_b32_e32 v143, v117
	v_fmac_f32_e32 v126, 0xba000000, v150
	v_fmac_f32_e32 v118, 0xba000000, v150
	v_mov_b32_e32 v140, v124
	v_mov_b32_e32 v141, v116
	v_pk_mul_f32 v[142:143], v[142:143], v[142:143]
	v_mov_b32_e32 v146, v127
	v_mov_b32_e32 v147, v119
	v_pk_fma_f32 v[140:141], v[140:141], v[140:141], v[142:143]
	v_mov_b32_e32 v142, v126
	v_mov_b32_e32 v143, v118
	v_pk_mul_f32 v[146:147], v[146:147], v[146:147]
	v_fmamk_f32 v121, v150, 0xba000000, v121
	v_pk_fma_f32 v[142:143], v[142:143], v[142:143], v[146:147]
	v_fmac_f32_e32 v120, 0xba000000, v150
	v_pk_add_f32 v[140:141], v[140:141], v[142:143]
	v_fmamk_f32 v123, v150, 0xba000000, v123
	v_fmac_f32_e32 v122, 0xba000000, v150
	v_pk_add_f32 v[140:141], v[140:141], v[140:141] op_sel_hi:[0,1]
	v_pk_mul_f32 v[142:143], v[122:123], v[122:123]
	v_pk_mul_f32 v[146:147], v[120:121], v[120:121]
	v_fmac_f32_e32 v108, 0xba000000, v150
	v_pk_mov_b32 v[148:149], v[146:147], v[142:143] op_sel:[1,0]
	v_mov_b32_e32 v147, v143
	v_fmamk_f32 v109, v150, 0xba000000, v109
	v_fmac_f32_e32 v110, 0xba000000, v150
	v_mul_f32_e32 v140, v108, v108
	v_pk_add_f32 v[142:143], v[148:149], v[146:147]
	v_fmamk_f32 v111, v150, 0xba000000, v111
	v_pk_fma_f32 v[146:147], v[108:109], v[108:109], v[140:141] op_sel_hi:[1,1,0]
	v_mul_f32_e32 v140, v110, v110
	v_pk_add_f32 v[142:143], v[142:143], v[142:143] op_sel_hi:[0,1]
	v_pk_fma_f32 v[148:149], v[110:111], v[110:111], v[140:141] op_sel_hi:[1,1,0]
	v_fmamk_f32 v115, v150, 0xba000000, v115
	v_fmac_f32_e32 v114, 0xba000000, v150
	v_fmamk_f32 v113, v150, 0xba000000, v113
	v_fmac_f32_e32 v112, 0xba000000, v150
	v_mul_f32_e32 v146, v112, v112
	v_mul_f32_e32 v148, v113, v113
	v_mul_f32_e32 v142, v114, v114
	v_mul_f32_e32 v140, v115, v115
	v_pk_add_f32 v[146:147], v[146:147], v[148:149]
	v_pk_add_f32 v[140:141], v[142:143], v[140:141]
	v_fmamk_f32 v101, v150, 0xba000000, v101
	v_pk_add_f32 v[140:141], v[146:147], v[140:141]
	v_fmac_f32_e32 v100, 0xba000000, v150
	v_fmamk_f32 v103, v150, 0xba000000, v103
	v_fmac_f32_e32 v102, 0xba000000, v150
	v_pk_add_f32 v[140:141], v[140:141], v[140:141] op_sel_hi:[0,1]
	v_pk_mul_f32 v[142:143], v[102:103], v[102:103]
	v_pk_mul_f32 v[146:147], v[100:101], v[100:101]
	v_fmac_f32_e32 v104, 0xba000000, v150
	v_pk_mov_b32 v[148:149], v[146:147], v[142:143] op_sel:[1,0]
	v_mov_b32_e32 v147, v143
	v_fmamk_f32 v105, v150, 0xba000000, v105
	v_fmac_f32_e32 v106, 0xba000000, v150
	v_mul_f32_e32 v140, v104, v104
	v_pk_add_f32 v[142:143], v[148:149], v[146:147]
	v_fmamk_f32 v107, v150, 0xba000000, v107
	v_pk_fma_f32 v[146:147], v[104:105], v[104:105], v[140:141] op_sel_hi:[1,1,0]
	v_mul_f32_e32 v140, v106, v106
	v_pk_add_f32 v[142:143], v[142:143], v[142:143] op_sel_hi:[0,1]
	v_pk_fma_f32 v[148:149], v[106:107], v[106:107], v[140:141] op_sel_hi:[1,1,0]
	v_fmamk_f32 v99, v150, 0xba000000, v99
	v_fmac_f32_e32 v98, 0xba000000, v150
	v_fmamk_f32 v97, v150, 0xba000000, v97
	v_fmac_f32_e32 v96, 0xba000000, v150
	v_mul_f32_e32 v146, v96, v96
	v_mul_f32_e32 v148, v97, v97
	v_mul_f32_e32 v142, v98, v98
	v_mul_f32_e32 v140, v99, v99
	v_pk_add_f32 v[146:147], v[146:147], v[148:149]
	v_pk_add_f32 v[140:141], v[142:143], v[140:141]
	s_nop 0
	v_pk_add_f32 v[140:141], v[146:147], v[140:141]
	s_nop 0
	v_add_f32_e32 v140, v140, v141
	s_waitcnt lgkmcnt(0)
	s_nop 1
	v_add_f32_dpp v140, v140, v140 quad_perm:[1,0,3,2] row_mask:0xf bank_mask:0xf
	s_nop 1
	v_add_f32_dpp v140, v140, v140 quad_perm:[2,3,0,1] row_mask:0xf bank_mask:0xf
	s_nop 1
	v_add_f32_dpp v140, v140, v140 row_half_mirror row_mask:0xf bank_mask:0xf
	s_nop 1
	v_add_f32_dpp v140, v140, v140 row_ror:8 row_mask:0xf bank_mask:0xf
	s_nop 0
	v_readlane_b32 s100, v140, 0
	v_readlane_b32 s101, v140, 16
	s_nop 0
	v_mov_b32_e32 v141, s100
	v_add_f32_e32 v141, s101, v141
	v_readlane_b32 s100, v140, 32
	v_readlane_b32 s101, v140, 48
	s_nop 0
	v_add_f32_e32 v141, s100, v141
	v_add_f32_e32 v140, s101, v141
	v_fmamk_f32 v140, v140, 0x3a000000, v229
	v_cmp_gt_f32_e32 vcc, s4, v140
	v_mul_f32_e32 v141, 0x4f800000, v140
	s_mov_b32 s4, 0xffff0000
	v_cndmask_b32_e32 v140, v140, v141, vcc
	v_sqrt_f32_e32 v141, v140
	s_nop 0
	v_add_u32_e32 v142, -1, v141
	v_fma_f32 v143, -v142, v141, v140
	v_cmp_ge_f32_e64 s[8:9], 0, v143
	v_add_u32_e32 v143, 1, v141
	s_nop 0
	v_cndmask_b32_e64 v142, v141, v142, s[8:9]
	v_fma_f32 v141, -v143, v141, v140
	v_cmp_lt_f32_e64 s[8:9], 0, v141
	s_nop 1
	v_cndmask_b32_e64 v141, v142, v143, s[8:9]
	v_mul_f32_e32 v142, 0x37800000, v141
	v_cndmask_b32_e32 v141, v141, v142, vcc
	v_cmp_class_f32_e32 vcc, v140, v230
	s_nop 1
	v_cndmask_b32_e32 v140, v141, v140, vcc
	v_div_scale_f32 v141, s[8:9], v140, v140, 1.0
	v_rcp_f32_e32 v142, v141
	s_nop 0
	v_fma_f32 v143, -v141, v142, 1.0
	v_fmac_f32_e32 v142, v143, v142
	v_div_scale_f32 v143, vcc, 1.0, v140, 1.0
	v_mul_f32_e32 v146, v143, v142
	v_fma_f32 v147, -v141, v146, v143
	v_fmac_f32_e32 v146, v147, v142
	v_fma_f32 v141, -v141, v146, v143
	v_div_fmas_f32 v141, v141, v142, v146
	ds_read_b128 v[146:149], v191 offset:24576
	ds_read_b128 v[150:153], v191 offset:32768
	v_div_fixup_f32 v140, v141, v140, 1.0
	v_pk_mul_f32 v[124:125], v[124:125], v[140:141] op_sel_hi:[1,0]
	v_pk_mul_f32 v[126:127], v[126:127], v[140:141] op_sel_hi:[1,0]
	s_waitcnt lgkmcnt(0)
	v_pk_add_f32 v[150:151], v[150:151], 1.0 op_sel_hi:[1,0]
	s_nop 0
	v_pk_fma_f32 v[124:125], v[150:151], v[124:125], v[146:147]
	v_pk_add_f32 v[142:143], v[152:153], 1.0 op_sel_hi:[1,0]
	v_bfe_u32 v141, v124, 16, 1
	v_add3_u32 v124, v124, v141, s69
	v_bfe_u32 v141, v125, 16, 1
	v_pk_fma_f32 v[126:127], v[142:143], v[126:127], v[148:149]
	v_lshrrev_b32_e32 v124, 16, v124
	v_add3_u32 v125, v125, v141, s69
	v_and_or_b32 v124, v125, s4, v124
	v_cvt_pk_bf16_f32 v125, v126, v127
	global_store_dwordx2 v[136:137], v[124:125], off
	ds_read_b128 v[124:127], v191 offset:25600
	ds_read_b128 v[146:149], v191 offset:33792
	v_pk_mul_f32 v[116:117], v[116:117], v[140:141] op_sel_hi:[1,0]
	v_pk_mul_f32 v[118:119], v[118:119], v[140:141] op_sel_hi:[1,0]
	v_pk_mul_f32 v[120:121], v[120:121], v[140:141] op_sel_hi:[1,0]
	v_pk_mul_f32 v[122:123], v[122:123], v[140:141] op_sel_hi:[1,0]
	s_waitcnt lgkmcnt(0)
	v_pk_add_f32 v[146:147], v[146:147], 1.0 op_sel_hi:[1,0]
	v_pk_add_f32 v[142:143], v[148:149], 1.0 op_sel_hi:[1,0]
	v_pk_fma_f32 v[116:117], v[146:147], v[116:117], v[124:125]
	v_pk_fma_f32 v[118:119], v[142:143], v[118:119], v[126:127]
	v_cvt_pk_bf16_f32 v116, v116, v117
	v_cvt_pk_bf16_f32 v117, v118, v119
	global_store_dwordx2 v[136:137], v[116:117], off offset:512
	ds_read_b128 v[116:119], v191 offset:26624
	ds_read_b128 v[124:127], v191 offset:34816
	v_pk_mul_f32 v[108:109], v[108:109], v[140:141] op_sel_hi:[1,0]
	v_pk_mul_f32 v[110:111], v[110:111], v[140:141] op_sel_hi:[1,0]
	v_pk_mul_f32 v[112:113], v[112:113], v[140:141] op_sel_hi:[1,0]
	v_pk_mul_f32 v[114:115], v[114:115], v[140:141] op_sel_hi:[1,0]
	s_waitcnt lgkmcnt(0)
	v_pk_add_f32 v[124:125], v[124:125], 1.0 op_sel_hi:[1,0]
	v_pk_add_f32 v[126:127], v[126:127], 1.0 op_sel_hi:[1,0]
	v_pk_fma_f32 v[116:117], v[124:125], v[120:121], v[116:117]
	v_pk_fma_f32 v[118:119], v[126:127], v[122:123], v[118:119]
	v_cvt_pk_bf16_f32 v116, v116, v117
	v_cvt_pk_bf16_f32 v117, v118, v119
	global_store_dwordx2 v[136:137], v[116:117], off offset:1024
	ds_read_b128 v[116:119], v191 offset:27648
	ds_read_b128 v[120:123], v191 offset:35840
	v_pk_mul_f32 v[100:101], v[100:101], v[140:141] op_sel_hi:[1,0]
	v_pk_mul_f32 v[102:103], v[102:103], v[140:141] op_sel_hi:[1,0]
	v_pk_mul_f32 v[104:105], v[104:105], v[140:141] op_sel_hi:[1,0]
	v_pk_mul_f32 v[106:107], v[106:107], v[140:141] op_sel_hi:[1,0]
	s_waitcnt lgkmcnt(0)
	v_pk_add_f32 v[120:121], v[120:121], 1.0 op_sel_hi:[1,0]
	v_pk_add_f32 v[122:123], v[122:123], 1.0 op_sel_hi:[1,0]
	v_pk_fma_f32 v[108:109], v[120:121], v[108:109], v[116:117]
	v_pk_fma_f32 v[110:111], v[122:123], v[110:111], v[118:119]
	v_cvt_pk_bf16_f32 v108, v108, v109
	v_cvt_pk_bf16_f32 v109, v110, v111
	global_store_dwordx2 v[136:137], v[108:109], off offset:1536
	ds_read_b128 v[108:111], v191 offset:28672
	ds_read_b128 v[116:119], v191 offset:36864
	v_pk_mul_f32 v[96:97], v[96:97], v[140:141] op_sel_hi:[1,0]
	v_pk_mul_f32 v[98:99], v[98:99], v[140:141] op_sel_hi:[1,0]
	s_waitcnt lgkmcnt(0)
	v_pk_add_f32 v[116:117], v[116:117], 1.0 op_sel_hi:[1,0]
	s_nop 0
	v_pk_fma_f32 v[108:109], v[116:117], v[112:113], v[108:109]
	v_pk_add_f32 v[118:119], v[118:119], 1.0 op_sel_hi:[1,0]
	v_pk_fma_f32 v[110:111], v[118:119], v[114:115], v[110:111]
	v_cvt_pk_bf16_f32 v108, v108, v109
	v_cvt_pk_bf16_f32 v109, v110, v111
	global_store_dwordx2 v[136:137], v[108:109], off offset:2048
	ds_read_b128 v[108:111], v191 offset:29696
	ds_read_b128 v[112:115], v191 offset:37888
	s_waitcnt lgkmcnt(0)
	v_pk_add_f32 v[112:113], v[112:113], 1.0 op_sel_hi:[1,0]
	s_nop 0
	v_pk_fma_f32 v[100:101], v[112:113], v[100:101], v[108:109]
	v_pk_add_f32 v[114:115], v[114:115], 1.0 op_sel_hi:[1,0]
	v_pk_fma_f32 v[102:103], v[114:115], v[102:103], v[110:111]
	v_cvt_pk_bf16_f32 v100, v100, v101
	v_cvt_pk_bf16_f32 v101, v102, v103
	global_store_dwordx2 v[136:137], v[100:101], off offset:2560
	ds_read_b128 v[100:103], v191 offset:30720
	ds_read_b128 v[108:111], v191 offset:38912
	s_waitcnt lgkmcnt(0)
	v_pk_add_f32 v[108:109], v[108:109], 1.0 op_sel_hi:[1,0]
	s_nop 0
	v_pk_fma_f32 v[100:101], v[108:109], v[104:105], v[100:101]
	v_pk_add_f32 v[110:111], v[110:111], 1.0 op_sel_hi:[1,0]
	v_pk_fma_f32 v[102:103], v[110:111], v[106:107], v[102:103]
	v_cvt_pk_bf16_f32 v100, v100, v101
	v_cvt_pk_bf16_f32 v101, v102, v103
	global_store_dwordx2 v[136:137], v[100:101], off offset:3072
	ds_read_b128 v[100:103], v191 offset:31744
	ds_read_b128 v[104:107], v191 offset:39936
	s_waitcnt lgkmcnt(0)
	v_pk_add_f32 v[104:105], v[104:105], 1.0 op_sel_hi:[1,0]
	s_nop 0
	v_pk_fma_f32 v[96:97], v[104:105], v[96:97], v[100:101]
	v_pk_add_f32 v[106:107], v[106:107], 1.0 op_sel_hi:[1,0]
	v_pk_fma_f32 v[98:99], v[106:107], v[98:99], v[102:103]
	v_cvt_pk_bf16_f32 v96, v96, v97
	v_cvt_pk_bf16_f32 v97, v98, v99
	global_store_dwordx2 v[136:137], v[96:97], off offset:3584

.LBB0_1295:
	v_readlane_b32 s4, v255, 15
	v_readlane_b32 s5, v255, 16
	s_and_b64 vcc, exec, s[4:5]
	s_cbranch_vccnz .LBB0_1225
	v_mov_b32_e32 v96, v64
	v_mov_b32_e32 v97, v68
	v_mov_b32_e32 v98, v65
	v_mov_b32_e32 v99, v69
	v_pk_add_f32 v[96:97], v[96:97], v[98:99]
	v_mov_b32_e32 v98, v66
	v_mov_b32_e32 v99, v70
	v_mov_b32_e32 v100, v67
	v_mov_b32_e32 v101, v71
	v_pk_add_f32 v[98:99], v[98:99], v[100:101]
	v_mov_b32_e32 v100, v72
	v_pk_add_f32 v[96:97], v[96:97], v[98:99]
	v_mov_b32_e32 v98, v73
	v_mov_b32_e32 v99, v74
	v_mov_b32_e32 v101, v75
	v_pk_add_f32 v[98:99], v[98:99], v[100:101]
	v_add_f32_e32 v97, 0, v97
	v_pk_add_f32 v[98:99], v[98:99], v[98:99] op_sel_hi:[0,1]
	v_add_f32_e32 v97, v96, v97
	v_add_f32_e32 v101, v76, v77
	v_add_f32_e32 v103, v78, v79
	v_mov_b32_e32 v100, v80
	v_mov_b32_e32 v102, v81
	v_mov_b32_e32 v98, v82
	v_mov_b32_e32 v96, v83
	v_pk_add_f32 v[100:101], v[100:101], v[102:103]
	v_pk_add_f32 v[96:97], v[98:99], v[96:97]
	v_mov_b32_e32 v98, v85
	v_pk_add_f32 v[96:97], v[100:101], v[96:97]
	v_mov_b32_e32 v99, v86
	v_mov_b32_e32 v100, v84
	v_mov_b32_e32 v101, v87
	v_pk_add_f32 v[98:99], v[98:99], v[100:101]
	v_pk_add_f32 v[96:97], v[96:97], v[96:97] op_sel_hi:[0,1]
	v_pk_add_f32 v[98:99], v[98:99], v[98:99] op_sel_hi:[0,1]
	v_add_f32_e32 v101, v88, v89
	v_add_f32_e32 v103, v90, v91
	v_mov_b32_e32 v100, v92
	v_mov_b32_e32 v102, v93
	v_mov_b32_e32 v98, v94
	v_mov_b32_e32 v96, v95
	v_pk_add_f32 v[100:101], v[100:101], v[102:103]
	v_pk_add_f32 v[96:97], v[98:99], v[96:97]
	v_mov_b32_e32 v140, v68
	v_pk_add_f32 v[96:97], v[100:101], v[96:97]
	v_mov_b32_e32 v152, v64
	v_add_f32_e32 v96, v96, v97
	ds_bpermute_b32 v97, v129, v96
	v_mov_b32_e32 v126, v70
	v_mov_b32_e32 v150, v66
	v_mov_b32_e32 v154, v72
	v_mov_b32_e32 v156, v74
	s_waitcnt lgkmcnt(0)
	v_add_f32_e32 v96, v96, v97
	ds_bpermute_b32 v97, v182, v96
	v_mov_b32_e32 v114, v76
	v_mov_b32_e32 v116, v78
	v_mov_b32_e32 v108, v82
	v_mov_b32_e32 v112, v80
	s_waitcnt lgkmcnt(0)
	v_add_f32_e32 v96, v96, v97
	ds_bpermute_b32 v97, v183, v96
	v_mov_b32_e32 v104, v84
	v_mov_b32_e32 v106, v86
	s_mov_b32 s4, 0xf800000
	s_lshr_b32 s6, s16, 12
	s_waitcnt lgkmcnt(0)
	v_add_f32_e32 v96, v96, v97
	ds_bpermute_b32 v97, v184, v96
	s_mulk_i32 s6, 0x6000
	s_waitcnt lgkmcnt(0)
	v_add_f32_e32 v96, v96, v97
	ds_bpermute_b32 v97, v185, v96
	s_waitcnt lgkmcnt(0)
	v_add_f32_e32 v96, v96, v97
	ds_bpermute_b32 v97, v186, v96
	s_waitcnt lgkmcnt(0)
	v_add_f32_e32 v124, v96, v97
	v_fmamk_f32 v141, v124, 0xba000000, v69
	v_fmamk_f32 v153, v124, 0xba000000, v65
	v_fmamk_f32 v127, v124, 0xba000000, v71
	v_fmac_f32_e32 v140, 0xba000000, v124
	v_fmamk_f32 v151, v124, 0xba000000, v67
	v_fmac_f32_e32 v152, 0xba000000, v124
	v_mov_b32_e32 v98, v141
	v_mov_b32_e32 v99, v153
	v_fmac_f32_e32 v126, 0xba000000, v124
	v_fmac_f32_e32 v150, 0xba000000, v124
	v_mov_b32_e32 v96, v140
	v_mov_b32_e32 v97, v152
	v_pk_mul_f32 v[98:99], v[98:99], v[98:99]
	v_mov_b32_e32 v100, v127
	v_mov_b32_e32 v101, v151
	v_pk_fma_f32 v[96:97], v[96:97], v[96:97], v[98:99]
	v_mov_b32_e32 v98, v126
	v_mov_b32_e32 v99, v150
	v_pk_mul_f32 v[100:101], v[100:101], v[100:101]
	v_fmamk_f32 v155, v124, 0xba000000, v73
	v_pk_fma_f32 v[98:99], v[98:99], v[98:99], v[100:101]
	v_fmac_f32_e32 v154, 0xba000000, v124
	v_pk_add_f32 v[96:97], v[96:97], v[98:99]
	v_fmamk_f32 v157, v124, 0xba000000, v75
	v_fmac_f32_e32 v156, 0xba000000, v124
	v_pk_add_f32 v[96:97], v[96:97], v[96:97] op_sel_hi:[0,1]
	v_pk_mul_f32 v[98:99], v[156:157], v[156:157]
	v_pk_mul_f32 v[100:101], v[154:155], v[154:155]
	v_fmac_f32_e32 v114, 0xba000000, v124
	v_pk_mov_b32 v[102:103], v[100:101], v[98:99] op_sel:[1,0]
	v_mov_b32_e32 v101, v99
	v_fmamk_f32 v115, v124, 0xba000000, v77
	v_fmac_f32_e32 v116, 0xba000000, v124
	v_mul_f32_e32 v96, v114, v114
	v_pk_add_f32 v[98:99], v[102:103], v[100:101]
	v_fmamk_f32 v117, v124, 0xba000000, v79
	v_pk_fma_f32 v[100:101], v[114:115], v[114:115], v[96:97] op_sel_hi:[1,1,0]
	v_mul_f32_e32 v96, v116, v116
	v_pk_add_f32 v[98:99], v[98:99], v[98:99] op_sel_hi:[0,1]
	v_pk_fma_f32 v[102:103], v[116:117], v[116:117], v[96:97] op_sel_hi:[1,1,0]
	v_fmamk_f32 v109, v124, 0xba000000, v83
	v_fmac_f32_e32 v108, 0xba000000, v124
	v_fmamk_f32 v113, v124, 0xba000000, v81
	v_fmac_f32_e32 v112, 0xba000000, v124
	v_mul_f32_e32 v100, v112, v112
	v_mul_f32_e32 v102, v113, v113
	v_mul_f32_e32 v98, v108, v108
	v_mul_f32_e32 v96, v109, v109
	v_pk_add_f32 v[100:101], v[100:101], v[102:103]
	v_pk_add_f32 v[96:97], v[98:99], v[96:97]
	v_fmamk_f32 v105, v124, 0xba000000, v85
	v_pk_add_f32 v[96:97], v[100:101], v[96:97]
	v_fmac_f32_e32 v104, 0xba000000, v124
	v_fmamk_f32 v107, v124, 0xba000000, v87
	v_fmac_f32_e32 v106, 0xba000000, v124
	v_pk_add_f32 v[110:111], v[96:97], v[96:97] op_sel_hi:[0,1]
	v_pk_mul_f32 v[96:97], v[106:107], v[106:107]
	v_pk_mul_f32 v[98:99], v[104:105], v[104:105]
	v_mov_b32_e32 v102, v90
	v_pk_mov_b32 v[100:101], v[98:99], v[96:97] op_sel:[1,0]
	v_mov_b32_e32 v99, v97
	v_pk_add_f32 v[96:97], v[100:101], v[98:99]
	v_mov_b32_e32 v100, v88
	v_fmac_f32_e32 v100, 0xba000000, v124
	v_pk_add_f32 v[118:119], v[96:97], v[96:97] op_sel_hi:[0,1]
	v_fmamk_f32 v101, v124, 0xba000000, v89
	v_fmac_f32_e32 v102, 0xba000000, v124
	v_mul_f32_e32 v96, v100, v100
	v_fmamk_f32 v103, v124, 0xba000000, v91
	v_pk_fma_f32 v[120:121], v[100:101], v[100:101], v[96:97] op_sel_hi:[1,1,0]
	v_mul_f32_e32 v96, v102, v102
	v_pk_fma_f32 v[122:123], v[102:103], v[102:103], v[96:97] op_sel_hi:[1,1,0]
	v_mov_b32_e32 v96, v94
	v_mov_b32_e32 v98, v92
	v_fmamk_f32 v97, v124, 0xba000000, v95
	v_fmac_f32_e32 v96, 0xba000000, v124
	v_fmamk_f32 v99, v124, 0xba000000, v93
	v_fmac_f32_e32 v98, 0xba000000, v124
	v_mul_f32_e32 v120, v98, v98
	v_mul_f32_e32 v122, v99, v99
	v_mul_f32_e32 v118, v96, v96
	v_mul_f32_e32 v110, v97, v97
	v_pk_add_f32 v[120:121], v[120:121], v[122:123]
	v_pk_add_f32 v[110:111], v[118:119], v[110:111]
	s_nop 0
	v_pk_add_f32 v[110:111], v[120:121], v[110:111]
	s_nop 0
	v_add_f32_e32 v110, v110, v111
	s_waitcnt lgkmcnt(0)
	s_nop 1
	v_add_f32_dpp v110, v110, v110 quad_perm:[1,0,3,2] row_mask:0xf bank_mask:0xf
	s_nop 1
	v_add_f32_dpp v110, v110, v110 quad_perm:[2,3,0,1] row_mask:0xf bank_mask:0xf
	s_nop 1
	v_add_f32_dpp v110, v110, v110 row_half_mirror row_mask:0xf bank_mask:0xf
	s_nop 1
	v_add_f32_dpp v110, v110, v110 row_ror:8 row_mask:0xf bank_mask:0xf
	s_nop 0
	v_readlane_b32 s100, v110, 0
	v_readlane_b32 s101, v110, 16
	s_nop 0
	v_mov_b32_e32 v111, s100
	v_add_f32_e32 v111, s101, v111
	v_readlane_b32 s100, v110, 32
	v_readlane_b32 s101, v110, 48
	s_nop 0
	v_add_f32_e32 v111, s100, v111
	v_add_f32_e32 v110, s101, v111
	v_fmamk_f32 v110, v110, 0x3a000000, v229
	v_mul_f32_e32 v111, 0x4f800000, v110
	v_cmp_gt_f32_e32 vcc, s4, v110
	s_mov_b32 s4, 0xffff0000
	s_nop 0
	v_cndmask_b32_e32 v110, v110, v111, vcc
	v_sqrt_f32_e32 v111, v110
	s_nop 0
	v_add_u32_e32 v118, -1, v111
	v_fma_f32 v119, -v118, v111, v110
	v_cmp_ge_f32_e64 s[8:9], 0, v119
	v_add_u32_e32 v119, 1, v111
	s_nop 0
	v_cndmask_b32_e64 v118, v111, v118, s[8:9]
	v_fma_f32 v111, -v119, v111, v110
	v_cmp_lt_f32_e64 s[8:9], 0, v111
	s_nop 1
	v_cndmask_b32_e64 v111, v118, v119, s[8:9]
	v_mul_f32_e32 v118, 0x37800000, v111
	v_cndmask_b32_e32 v111, v111, v118, vcc
	v_cmp_class_f32_e32 vcc, v110, v230
	s_nop 1
	v_cndmask_b32_e32 v110, v111, v110, vcc
	v_div_scale_f32 v111, s[8:9], v110, v110, 1.0
	v_rcp_f32_e32 v118, v111
	s_lshl_b64 s[8:9], s[16:17], 11
	v_fma_f32 v119, -v111, v118, 1.0
	v_fmac_f32_e32 v118, v119, v118
	v_div_scale_f32 v119, vcc, 1.0, v110, 1.0
	v_mul_f32_e32 v120, v119, v118
	v_fma_f32 v121, -v111, v120, v119
	v_fmac_f32_e32 v120, v121, v118
	v_fma_f32 v111, -v111, v120, v119
	v_div_fmas_f32 v111, v111, v118, v120
	v_div_fixup_f32 v110, v111, v110, 1.0
	v_add_u32_e32 v111, s6, v187
	ds_read_b128 v[118:121], v111 offset:32768
	ds_read_b128 v[122:125], v111 offset:24576
	v_pk_mul_f32 v[158:159], v[140:141], v[110:111] op_sel_hi:[1,0]
	v_pk_mul_f32 v[126:127], v[126:127], v[110:111] op_sel_hi:[1,0]
	ds_read_b128 v[140:143], v111 offset:33792
	ds_read_b128 v[146:149], v111 offset:25600
	s_waitcnt lgkmcnt(3)
	v_pk_add_f32 v[118:119], v[118:119], 1.0 op_sel_hi:[1,0]
	v_pk_add_f32 v[120:121], v[120:121], 1.0 op_sel_hi:[1,0]
	s_waitcnt lgkmcnt(2)
	v_pk_fma_f32 v[118:119], v[118:119], v[158:159], v[122:123]
	v_pk_fma_f32 v[120:121], v[120:121], v[126:127], v[124:125]
	v_cvt_pk_bf16_f32 v122, v118, v119
	v_cvt_pk_bf16_f32 v123, v120, v121
	v_lshl_add_u64 v[118:119], s[8:9], 1, v[134:135]
	v_pk_mul_f32 v[120:121], v[152:153], v[110:111] op_sel_hi:[1,0]
	s_waitcnt lgkmcnt(1)
	v_pk_add_f32 v[126:127], v[140:141], 1.0 op_sel_hi:[1,0]
	global_store_dwordx2 v[118:119], v[122:123], off
	v_pk_mul_f32 v[122:123], v[150:151], v[110:111] op_sel_hi:[1,0]
	v_pk_add_f32 v[124:125], v[142:143], 1.0 op_sel_hi:[1,0]
	s_waitcnt lgkmcnt(0)
	v_pk_fma_f32 v[120:121], v[126:127], v[120:121], v[146:147]
	v_pk_fma_f32 v[122:123], v[124:125], v[122:123], v[148:149]
	v_cvt_pk_bf16_f32 v120, v120, v121
	v_cvt_pk_bf16_f32 v121, v122, v123
	global_store_dwordx2 v[118:119], v[120:121], off offset:512
	ds_read_b128 v[120:123], v111 offset:34816
	ds_read_b128 v[124:127], v111 offset:26624
	v_pk_mul_f32 v[146:147], v[154:155], v[110:111] op_sel_hi:[1,0]
	v_pk_mul_f32 v[148:149], v[156:157], v[110:111] op_sel_hi:[1,0]
	ds_read_b128 v[140:143], v111 offset:35840
	s_waitcnt lgkmcnt(2)
	v_pk_add_f32 v[152:153], v[120:121], 1.0 op_sel_hi:[1,0]
	v_pk_add_f32 v[150:151], v[122:123], 1.0 op_sel_hi:[1,0]
	s_waitcnt lgkmcnt(1)
	v_pk_fma_f32 v[124:125], v[152:153], v[146:147], v[124:125]
	ds_read_b128 v[120:123], v111 offset:27648
	v_pk_fma_f32 v[126:127], v[150:151], v[148:149], v[126:127]
	v_cvt_pk_bf16_f32 v124, v124, v125
	v_cvt_pk_bf16_f32 v125, v126, v127
	v_pk_mul_f32 v[114:115], v[114:115], v[110:111] op_sel_hi:[1,0]
	s_waitcnt lgkmcnt(1)
	v_pk_add_f32 v[126:127], v[140:141], 1.0 op_sel_hi:[1,0]
	global_store_dwordx2 v[118:119], v[124:125], off offset:1024
	s_waitcnt lgkmcnt(0)
	v_pk_fma_f32 v[114:115], v[126:127], v[114:115], v[120:121]
	v_pk_mul_f32 v[116:117], v[116:117], v[110:111] op_sel_hi:[1,0]
	v_pk_add_f32 v[124:125], v[142:143], 1.0 op_sel_hi:[1,0]
	v_pk_fma_f32 v[116:117], v[124:125], v[116:117], v[122:123]
	v_cvt_pk_bf16_f32 v114, v114, v115
	v_cvt_pk_bf16_f32 v115, v116, v117
	global_store_dwordx2 v[118:119], v[114:115], off offset:1536
	ds_read_b128 v[114:117], v111 offset:36864
	ds_read_b128 v[120:123], v111 offset:28672
	v_pk_mul_f32 v[140:141], v[112:113], v[110:111] op_sel_hi:[1,0]
	v_pk_mul_f32 v[108:109], v[108:109], v[110:111] op_sel_hi:[1,0]
	ds_read_b128 v[124:127], v111 offset:37888
	s_waitcnt lgkmcnt(2)
	v_pk_add_f32 v[116:117], v[116:117], 1.0 op_sel_hi:[1,0]
	v_pk_add_f32 v[142:143], v[114:115], 1.0 op_sel_hi:[1,0]
	s_waitcnt lgkmcnt(1)
	v_pk_fma_f32 v[108:109], v[116:117], v[108:109], v[122:123]
	v_pk_fma_f32 v[116:117], v[142:143], v[140:141], v[120:121]
	ds_read_b128 v[112:115], v111 offset:29696
	v_cvt_pk_bf16_f32 v116, v116, v117
	v_cvt_pk_bf16_f32 v117, v108, v109
	global_store_dwordx2 v[118:119], v[116:117], off offset:2048
	v_pk_mul_f32 v[104:105], v[104:105], v[110:111] op_sel_hi:[1,0]
	s_waitcnt lgkmcnt(1)
	v_pk_add_f32 v[116:117], v[124:125], 1.0 op_sel_hi:[1,0]
	v_pk_mul_f32 v[106:107], v[106:107], v[110:111] op_sel_hi:[1,0]
	v_pk_add_f32 v[108:109], v[126:127], 1.0 op_sel_hi:[1,0]
	s_waitcnt lgkmcnt(0)
	v_pk_fma_f32 v[104:105], v[116:117], v[104:105], v[112:113]
	v_pk_fma_f32 v[106:107], v[108:109], v[106:107], v[114:115]
	v_cvt_pk_bf16_f32 v104, v104, v105
	v_cvt_pk_bf16_f32 v105, v106, v107
	global_store_dwordx2 v[118:119], v[104:105], off offset:2560
	ds_read_b128 v[104:107], v111 offset:38912
	ds_read_b128 v[112:115], v111 offset:30720
	v_pk_mul_f32 v[108:109], v[100:101], v[110:111] op_sel_hi:[1,0]
	v_pk_mul_f32 v[116:117], v[102:103], v[110:111] op_sel_hi:[1,0]
	ds_read_b128 v[100:103], v111 offset:39936
	s_waitcnt lgkmcnt(2)
	v_pk_add_f32 v[122:123], v[104:105], 1.0 op_sel_hi:[1,0]
	v_pk_add_f32 v[120:121], v[106:107], 1.0 op_sel_hi:[1,0]
	s_waitcnt lgkmcnt(1)
	v_pk_fma_f32 v[108:109], v[122:123], v[108:109], v[112:113]
	ds_read_b128 v[104:107], v111 offset:31744
	v_pk_fma_f32 v[114:115], v[120:121], v[116:117], v[114:115]
	v_bfe_u32 v111, v115, 16, 1
	v_add3_u32 v111, v115, v111, s69
	v_pk_mul_f32 v[98:99], v[98:99], v[110:111] op_sel_hi:[1,0]
	s_waitcnt lgkmcnt(1)
	v_pk_add_f32 v[100:101], v[100:101], 1.0 op_sel_hi:[1,0]
	v_pk_mul_f32 v[96:97], v[96:97], v[110:111] op_sel_hi:[1,0]
	s_waitcnt lgkmcnt(0)
	v_pk_fma_f32 v[98:99], v[100:101], v[98:99], v[104:105]
	v_pk_add_f32 v[102:103], v[102:103], 1.0 op_sel_hi:[1,0]
	v_pk_fma_f32 v[96:97], v[102:103], v[96:97], v[106:107]
	v_cvt_pk_bf16_f32 v108, v108, v109
	v_bfe_u32 v109, v114, 16, 1
	v_cvt_pk_bf16_f32 v98, v98, v99
	v_add3_u32 v109, v114, v109, s69
	v_lshrrev_b32_e32 v109, 16, v109
	v_and_or_b32 v109, v111, s4, v109
	v_cvt_pk_bf16_f32 v99, v96, v97
	global_store_dwordx2 v[118:119], v[108:109], off offset:3072
	global_store_dwordx2 v[118:119], v[98:99], off offset:3584
	s_branch .LBB0_1225
